# row pass after FFN1 (old phase 3) fused into the GEMM2 phase: per-M-tile counters instead of the grid barrier, hand-written row pass on the own 64 rows, sample rows by WGs 44-59
# speedup vs baseline: 1.0010x; 1.0001x over previous
; #define PG8_STAGE(bufoff, gbase, voff) do { _Pragma("unroll") for (int _i = 0; _i < 2; ++_i) \
;         __builtin_amdgcn_global_load_lds((const unsigned*)((const char*)(gbase) + (voff)[_i]), (PG8_LAS unsigned*)(lds + (bufoff) + ldsw + _i * 8192), 16, 0, 0); } while (0)
; #define PG8_WAIT_V(n) asm volatile("s_waitcnt vmcnt(" #n ")" ::: "memory")
; #define PG8_BAR __builtin_amdgcn_s_barrier()
;     __device__ __forceinline__ unsigned char* ws() const { return (unsigned char*)ptr(37); }
; #define ws (p.ws())
; #define SEAM(k) do { if (IN(k) && IN((k) + 1)) xcd_barrier(bar); } while (0)
; template <class Epi, class Sched, bool ALIGN_EPI = false, bool SP2 = false>
; __device__ __forceinline__ void gemm_phase(PG8_LAS unsigned char* lds, const Gemm g, const Sched& S, const Epi& E) {
;     ...
;     const char* cA = (const char*)g.A + (size_t)cur.pm * tstep; const char* cB = (const char*)g.Bt + (size_t)cur.pn * tstep;
;     S.a_ready(cur);
;     if constexpr (SP2) {
;         PG8_STAGE(PG8_SB(0, 0), cB, voffB); PG8_STAGE(PG8_SB(0, 1), cB + hstep, voffB); PG8_STAGE(PG8_SA(0, 0), cA, voffA); PG8_STAGE(PG8_SA(0, 1), cA + hstep, voffA);
;         if (wr == 1) PG8_BAR;
;         PG8_WAIT_V(2); PG8_BAR;
;         PG8_STAGE(PG8_SB(1, 0), cB + kstep, voffB); PG8_STAGE(PG8_SA(1, 0), cA + kstep, voffA); PG8_STAGE(PG8_SB(1, 1), cB + hstep + kstep, voffB);
;         PG8_WAIT_V(6); PG8_BAR;
;     } else {
;         PG8_STAGE(PG8_SB(0, 0), cB, voffB); PG8_STAGE(PG8_SA(0, 0), cA, voffA); PG8_STAGE(PG8_SB(0, 1), cB + hstep, voffB); PG8_STAGE(PG8_SA(0, 1), cA + hstep, voffA);
;         if (wr == 1) PG8_BAR;
;         PG8_WAIT_V(4); PG8_BAR;
;         PG8_STAGE(PG8_SB(1, 0), cB + kstep, voffB); PG8_STAGE(PG8_SA(1, 0), cA + kstep, voffA); PG8_STAGE(PG8_SB(1, 1), cB + hstep + kstep, voffB);
;         PG8_WAIT_V(6); PG8_BAR;
; __global__ void __launch_bounds__(512) fwd_kernel(Params prm) {
;     ...
;     if (IN(2)) { EpiF32 E{(float*)(ws + WS_F)}; run_gemm(lds, (const bf16_t*)(ws + WS_G), (const bf16_t*)(ws + WS_W2T), DM, DFF, E, MPR); run_gemm_sample(lds, (const bf16_t*)(ws + WS_G), (const bf16_t*)(ws + WS_W2T), DFF, (float*)(ws + WS_PART)); } SEAM(2);
.LBB0_329:
	s_waitcnt lgkmcnt(0)
	v_readfirstlane_b32 s14, v0
	v_readfirstlane_b32 s16, v1
	v_cmp_eq_u32_e32 vcc, 0, v180
	s_and_saveexec_b64 s[46:47], vcc
	s_cbranch_execz .Lfrp3_sigA
	buffer_wbl2 sc1
	s_waitcnt vmcnt(0)
	s_and_b32 s42, s28, 7
	s_lshl_b32 s42, s42, 3
	s_bfe_u32 s43, s28, 0x30003
	s_add_i32 s42, s42, s43
	s_lshl_b32 s42, s42, 2
	v_mov_b32_e32 v230, s42
	s_add_u32 s44, s30, 0x3180400
	s_addc_u32 s45, s31, 0
	v_mov_b32_e32 v231, 1
	global_atomic_add v230, v231, s[44:45]
.Lfrp3_sigA:
	s_or_b64 exec, exec, s[46:47]
	s_cmp_gt_i32 s28, 43
	v_readfirstlane_b32 s10, v180
	s_cbranch_scc1 .LBB0_335
	s_ashr_i32 s8, s28, 2
	s_ashr_i32 s9, s8, 31
	s_and_b32 s11, s28, 3
	s_lshl_b64 s[2:3], s[8:9], 9
	s_add_u32 s13, s14, s2
	s_addc_u32 s15, s16, s3
	s_add_u32 s2, s13, 0xaa80000
	s_addc_u32 s3, s15, 0
	s_lshr_b32 s17, s10, 6
	s_lshr_b32 s22, s10, 8
	s_lshl_b32 s21, s17, 10
	s_mul_i32 s4, s11, 0x160000
	s_add_u32 s18, s13, s4
	s_addc_u32 s19, s15, 0
	s_add_u32 s4, s18, 0xb00000
	s_addc_u32 s5, s19, 0
	s_add_i32 s12, s21, 0
	s_add_i32 m0, s12, 0x10000
	v_mov_b32_e32 v129, 0
	global_load_lds_dwordx4 v128, s[4:5]
	s_add_i32 m0, s12, 0x12000
	s_add_u32 s18, s18, 0xbb0000
	global_load_lds_dwordx4 v130, s[4:5]
	s_addc_u32 s19, s19, 0
	s_add_i32 m0, s12, 0x14000
	s_add_i32 s20, s12, 0x2000
	global_load_lds_dwordx4 v128, s[18:19]
	s_add_i32 m0, s12, 0x16000
	s_add_u32 s24, s13, 0xab30000
	global_load_lds_dwordx4 v130, s[18:19]
	s_mov_b32 m0, s12
	s_addc_u32 s25, s15, 0
	global_load_lds_dwordx4 v128, s[2:3]
	s_mov_b32 m0, s20
	s_add_i32 s13, s12, 0x4000
	global_load_lds_dwordx4 v130, s[2:3]
	s_mov_b32 m0, s13
	s_add_i32 s15, s12, 0x6000
	global_load_lds_dwordx4 v128, s[24:25]
	s_mov_b32 m0, s15
	v_mov_b32_e32 v131, v129
	global_load_lds_dwordx4 v130, s[24:25]
	v_lshl_add_u64 v[32:33], s[4:5], 0, v[128:129]
	v_lshl_add_u64 v[34:35], s[4:5], 0, v[130:131]
	v_lshl_add_u64 v[30:31], s[18:19], 0, v[128:129]
	v_lshl_add_u64 v[26:27], s[18:19], 0, v[130:131]
	v_lshl_add_u64 v[24:25], s[2:3], 0, v[128:129]
	v_lshl_add_u64 v[22:23], s[2:3], 0, v[130:131]
	v_lshl_add_u64 v[12:13], s[24:25], 0, v[128:129]
	s_cmp_lg_u32 s22, 1
	v_lshl_add_u64 v[14:15], s[24:25], 0, v[130:131]
	s_cbranch_scc1 .LBB0_332
	s_barrier

;     __device__ __forceinline__ float* out() const { return (float*)ptr(36); }
; __device__ __forceinline__ const float* xrow_ptr(const Ctx& p, int row) { return row < MPR ? p.in(0) + (size_t)row * DM : p.in(1) + (size_t)(row - MPR) * DM; }
; __device__ __forceinline__ void phase_rowpass(const Ctx& p, const float* F, int base_is_x, float alpha, const float* gpost, const float* gnext, bf16_t* XN, const float* PART, int nsplit) {
;     const int tid = threadIdx.x, lane = tid & 63, wave = __builtin_amdgcn_readfirstlane(tid >> 6);
;     const int gw = blockIdx.x * 8 + wave, NGW = gridDim.x * 8;
;     float* H = p.out() + O_Y;
;     auto loadrow = [&](int m, f32x4 (&f)[4], f32x4 (&b)[4]) {
;         const f32x4* fr = (const f32x4*)(F + (size_t)m * DM) + lane;
;         const f32x4* br = (const f32x4*)(base_is_x ? xrow_ptr(p, m) : H + (size_t)m * DM) + lane;
; #pragma unroll
;         for (int j = 0; j < 4; ++j) { b[j] = br[64 * j];
;             if (m < MPR) f[j] = fr[64 * j];
;             else { f[j] = (f32x4){0.f, 0.f, 0.f, 0.f};
;                 for (int ks = 0; ks < nsplit; ++ks) f[j] = f[j] + ((const f32x4*)(PART + ((size_t)ks * 128 + (m - MPR)) * DM))[lane + 64 * j]; } }
;     };
;     f32x4 gp[4], gn[4];
; #pragma unroll
;     for (int j = 0; j < 4; ++j) { gp[j] = ((const f32x4*)gpost)[lane + 64 * j]; gn[j] = gnext ? ((const f32x4*)gnext)[lane + 64 * j] : (f32x4){0.f, 0.f, 0.f, 0.f}; }
;     f32x4 f[4], b[4], f2[4], b2[4];
;     if (gw < MR) loadrow(gw, f, b);
.LBB0_334:
	s_barrier
	v_cmp_eq_u32_e32 vcc, 0, v180
	s_and_saveexec_b64 s[46:47], vcc
	s_cbranch_execz .Lfrp3_sigB
	buffer_wbl2 sc1
	s_waitcnt vmcnt(0)
	v_mov_b32_e32 v230, 0
	s_add_u32 s44, s30, 0x3180500
	s_addc_u32 s45, s31, 0
	v_mov_b32_e32 v231, 1
	global_atomic_add v230, v231, s[44:45]
.Lfrp3_sigB:
	s_or_b64 exec, exec, s[46:47]
.LBB0_335:
.Lfrp3:
	v_mov_b32_e32 v0, 0x23520
	v_mov_b32_e32 v1, 0x23448
	ds_read_b64 v[2:3], v0
	ds_read_b64 v[4:5], v1
	v_mov_b32_e32 v1, 0x23450
	ds_read_b64 v[6:7], v1
	v_mov_b32_e32 v1, 0x23400
	ds_read_b128 v[8:11], v1
	v_readfirstlane_b32 s2, v180
	s_waitcnt lgkmcnt(0)
	v_readfirstlane_b32 s8, v2
	v_readfirstlane_b32 s9, v3
	v_readfirstlane_b32 s10, v4
	v_readfirstlane_b32 s11, v5
	v_readfirstlane_b32 s12, v6
	v_readfirstlane_b32 s13, v7
	v_readfirstlane_b32 s14, v8
	v_readfirstlane_b32 s15, v9
	v_readfirstlane_b32 s16, v10
	v_readfirstlane_b32 s17, v11
	s_nop 4
	s_lshr_b32 s20, s2, 6
	v_and_b32_e32 v0, 63, v180
	v_lshlrev_b32_e32 v144, 4, v0
	v_lshlrev_b32_e32 v145, 3, v0
	v_mov_b32_e32 v146, 0x358637bd
	v_mov_b32_e32 v147, 0x260
	s_mov_b32 s33, 0xf800000
	global_load_dwordx4 v[112:115], v144, s[10:11] offset:0
	global_load_dwordx4 v[116:119], v144, s[10:11] offset:1024
	global_load_dwordx4 v[120:123], v144, s[10:11] offset:2048
	global_load_dwordx4 v[124:127], v144, s[10:11] offset:3072
	global_load_dwordx4 v[128:131], v144, s[12:13] offset:0
	global_load_dwordx4 v[132:135], v144, s[12:13] offset:1024
	global_load_dwordx4 v[136:139], v144, s[12:13] offset:2048
	global_load_dwordx4 v[140:143], v144, s[12:13] offset:3072
	v_cmp_eq_u32_e32 vcc, 0, v180
	s_and_saveexec_b64 s[46:47], vcc
	s_cbranch_execz .Lfrp3_wa_done
	s_and_b32 s42, s28, 7
	s_lshl_b32 s42, s42, 3
	s_bfe_u32 s43, s28, 0x30003
	s_add_i32 s42, s42, s43
	s_lshl_b32 s42, s42, 2
	v_mov_b32_e32 v230, s42
	s_add_u32 s44, s30, 0x3180400
	s_addc_u32 s45, s31, 0
.Lfrp3_wa_spin:
	global_load_dword v231, v230, s[44:45] sc1
	s_waitcnt vmcnt(0)
	v_cmp_gt_u32_e32 vcc, 4, v231
	s_cbranch_vccz .Lfrp3_wa_ok
	s_sleep 2
	s_branch .Lfrp3_wa_spin

; __device__ __forceinline__ void phase_rowpass(const Ctx& p, const float* F, int base_is_x, float alpha, const float* gpost, const float* gnext, bf16_t* XN, const float* PART, int nsplit) {
;     ...
;     for (int m = gw; m < MR; m += NGW) {
;         const bool more = m + NGW < MR;
;         if (more) loadrow(m + NGW, f2, b2);
;         float s = 0.f;
; #pragma unroll
;         for (int j = 0; j < 4; ++j) s += (f[j].x * f[j].x + f[j].y * f[j].y) + (f[j].z * f[j].z + f[j].w * f[j].w);
;         const float rs = alpha / sqrtf(wave_sum_fast(s) * (1.f / DM) + EPS);
;         float s2 = 0.f;
; #pragma unroll
;         for (int j = 0; j < 4; ++j) { b[j] = b[j] + f[j] * rs * gp[j]; s2 += (b[j].x * b[j].x + b[j].y * b[j].y) + (b[j].z * b[j].z + b[j].w * b[j].w);
;             ((f32x4*)(H + (size_t)m * DM))[lane + 64 * j] = b[j]; }
.Lfrp3_wa_done:
	s_or_b64 exec, exec, s[46:47]
	s_barrier
	s_and_b32 s42, s28, 7
	s_lshl_b32 s42, s42, 3
	s_bfe_u32 s43, s28, 0x30003
	s_add_i32 s42, s42, s43
	s_lshr_b32 s43, s28, 6
	s_lshl_b32 s42, s42, 8
	s_lshl_b32 s43, s43, 6
	s_add_i32 s42, s42, s43
	s_lshl_b32 s43, s20, 3
	s_add_i32 s23, s42, s43
	s_lshl_b32 s21, s23, 12
	s_add_u32 s40, s8, s21
	s_addc_u32 s41, s9, 0
	s_lshl_b32 s22, s23, 11
	s_add_u32 s42, s30, s22
	s_addc_u32 s43, s31, 0
	s_add_u32 s42, s42, 0x3200000
	s_addc_u32 s43, s43, 0
	s_add_u32 s24, s30, s21
	s_addc_u32 s25, s31, 0
	s_add_u32 s24, s24, 0xabe0000
	s_addc_u32 s25, s25, 0
	s_add_u32 s26, s14, s21
	s_addc_u32 s27, s15, 0
	global_load_dwordx4 v[0:3], v144, s[24:25] offset:0
	global_load_dwordx4 v[4:7], v144, s[24:25] offset:1024
	global_load_dwordx4 v[8:11], v144, s[24:25] offset:2048
	global_load_dwordx4 v[12:15], v144, s[24:25] offset:3072
	global_load_dwordx4 v[16:19], v144, s[26:27] offset:0
	global_load_dwordx4 v[20:23], v144, s[26:27] offset:1024
	global_load_dwordx4 v[24:27], v144, s[26:27] offset:2048
	global_load_dwordx4 v[28:31], v144, s[26:27] offset:3072
	s_add_u32 s24, s24, 0x1000
	s_addc_u32 s25, s25, 0
	s_add_u32 s26, s26, 0x1000
	s_addc_u32 s27, s27, 0
	global_load_dwordx4 v[32:35], v144, s[24:25] offset:0
	global_load_dwordx4 v[36:39], v144, s[24:25] offset:1024
	global_load_dwordx4 v[40:43], v144, s[24:25] offset:2048
	global_load_dwordx4 v[44:47], v144, s[24:25] offset:3072
	global_load_dwordx4 v[48:51], v144, s[26:27] offset:0
	global_load_dwordx4 v[52:55], v144, s[26:27] offset:1024
	global_load_dwordx4 v[56:59], v144, s[26:27] offset:2048
	global_load_dwordx4 v[60:63], v144, s[26:27] offset:3072
	s_add_u32 s24, s24, 0x1000
	s_addc_u32 s25, s25, 0
	s_add_u32 s26, s26, 0x1000
	s_addc_u32 s27, s27, 0
	global_load_dwordx4 v[64:67], v144, s[24:25] offset:0
	global_load_dwordx4 v[68:71], v144, s[24:25] offset:1024
	global_load_dwordx4 v[72:75], v144, s[24:25] offset:2048
	global_load_dwordx4 v[76:79], v144, s[24:25] offset:3072
	global_load_dwordx4 v[80:83], v144, s[26:27] offset:0
	global_load_dwordx4 v[84:87], v144, s[26:27] offset:1024
	global_load_dwordx4 v[88:91], v144, s[26:27] offset:2048
	global_load_dwordx4 v[92:95], v144, s[26:27] offset:3072
	s_add_u32 s24, s24, 0x1000
	s_addc_u32 s25, s25, 0
	s_add_u32 s26, s26, 0x1000
	s_addc_u32 s27, s27, 0
	s_waitcnt vmcnt(16)
	v_mul_f32_e32 v96, v1, v1
	v_mul_f32_e32 v98, v3, v3
	v_fmac_f32_e32 v96, v0, v0
	v_fmac_f32_e32 v98, v2, v2
	v_add_f32_e32 v96, v96, v98
	v_mul_f32_e32 v97, v5, v5
	v_mul_f32_e32 v98, v7, v7
	v_fmac_f32_e32 v97, v4, v4
	v_fmac_f32_e32 v98, v6, v6
	v_add_f32_e32 v97, v97, v98
	v_add_f32_e32 v96, v97, v96
	v_mul_f32_e32 v97, v9, v9
	v_mul_f32_e32 v98, v11, v11
	v_fmac_f32_e32 v97, v8, v8
	v_fmac_f32_e32 v98, v10, v10
	v_add_f32_e32 v97, v97, v98
	v_add_f32_e32 v96, v97, v96
	v_mul_f32_e32 v97, v13, v13
	v_mul_f32_e32 v98, v15, v15
	v_fmac_f32_e32 v97, v12, v12
	v_fmac_f32_e32 v98, v14, v14
	v_add_f32_e32 v97, v97, v98
	v_add_f32_e32 v96, v97, v96
	s_nop 1
	v_add_f32_dpp v96, v96, v96 quad_perm:[1,0,3,2] row_mask:0xf bank_mask:0xf bound_ctrl:1
	s_nop 1
	v_add_f32_dpp v96, v96, v96 quad_perm:[2,3,0,1] row_mask:0xf bank_mask:0xf bound_ctrl:1
	s_nop 1
	v_add_f32_dpp v96, v96, v96 row_half_mirror row_mask:0xf bank_mask:0xf bound_ctrl:1
	s_nop 1
	v_add_f32_dpp v96, v96, v96 row_mirror row_mask:0xf bank_mask:0xf bound_ctrl:1
	v_mov_b32_e32 v97, v96
	s_nop 1
	v_permlane16_swap_b32_e32 v96, v97
	v_add_f32_e32 v96, v96, v97
	v_mov_b32_e32 v97, v96
	s_nop 1
	v_permlane32_swap_b32_e32 v96, v97
	v_add_f32_e32 v96, v96, v97
	v_fmamk_f32 v96, v96, 0x3a800000, v146
	v_mul_f32_e32 v97, 0x4f800000, v96
	v_cmp_gt_f32_e32 vcc, s33, v96
	s_nop 1
	v_cndmask_b32_e32 v96, v96, v97, vcc
	v_sqrt_f32_e32 v97, v96
	s_nop 0
	v_add_u32_e32 v98, -1, v97
	v_fma_f32 v99, -v98, v97, v96
	v_cmp_ge_f32_e64 s[4:5], 0, v99
	v_add_u32_e32 v99, 1, v97
	s_nop 0
	v_cndmask_b32_e64 v98, v97, v98, s[4:5]
	v_fma_f32 v97, -v99, v97, v96
	v_cmp_lt_f32_e64 s[4:5], 0, v97
	s_nop 1
	v_cndmask_b32_e64 v97, v98, v99, s[4:5]
	v_mul_f32_e32 v98, 0x37800000, v97
	v_cndmask_b32_e32 v97, v97, v98, vcc
	v_cmp_class_f32_e32 vcc, v96, v147
	s_nop 1
	v_cndmask_b32_e32 v96, v97, v96, vcc
	v_div_scale_f32 v97, s[4:5], v96, v96, 0.5
	v_rcp_f32_e32 v98, v97
	s_nop 0
	v_fma_f32 v99, -v97, v98, 1.0
	v_fmac_f32_e32 v98, v99, v98
	v_div_scale_f32 v99, vcc, 0.5, v96, 0.5
	v_mul_f32_e32 v100, v99, v98
	v_fma_f32 v101, -v97, v100, v99
	v_fmac_f32_e32 v100, v101, v98
	v_fma_f32 v97, -v97, v100, v99
	v_div_fmas_f32 v97, v97, v98, v100
	v_div_fixup_f32 v96, v97, v96, 0.5
	v_mul_f32_e32 v0, v0, v96
	v_mul_f32_e32 v1, v1, v96
	v_mul_f32_e32 v2, v2, v96
	v_mul_f32_e32 v3, v3, v96
	v_mul_f32_e32 v4, v4, v96
	v_mul_f32_e32 v5, v5, v96
	v_mul_f32_e32 v6, v6, v96
	v_mul_f32_e32 v7, v7, v96
	v_mul_f32_e32 v8, v8, v96
	v_mul_f32_e32 v9, v9, v96
	v_mul_f32_e32 v10, v10, v96
	v_mul_f32_e32 v11, v11, v96
	v_mul_f32_e32 v12, v12, v96
	v_mul_f32_e32 v13, v13, v96
	v_mul_f32_e32 v14, v14, v96
	v_mul_f32_e32 v15, v15, v96
	v_fmac_f32_e32 v16, v112, v0
	v_fmac_f32_e32 v17, v113, v1
	v_fmac_f32_e32 v18, v114, v2
	v_fmac_f32_e32 v19, v115, v3
	v_fmac_f32_e32 v20, v116, v4
	v_fmac_f32_e32 v21, v117, v5
	v_fmac_f32_e32 v22, v118, v6
	v_fmac_f32_e32 v23, v119, v7
	v_fmac_f32_e32 v24, v120, v8
	v_fmac_f32_e32 v25, v121, v9
	v_fmac_f32_e32 v26, v122, v10
	v_fmac_f32_e32 v27, v123, v11
	v_fmac_f32_e32 v28, v124, v12
	v_fmac_f32_e32 v29, v125, v13
	v_fmac_f32_e32 v30, v126, v14
	v_fmac_f32_e32 v31, v127, v15
	global_store_dwordx4 v144, v[16:19], s[40:41] offset:0
	global_store_dwordx4 v144, v[20:23], s[40:41] offset:1024
; __device__ __forceinline__ unsigned pk2(float lo, float hi) { f32x2 v = {lo, hi}; bf16x2_t b = __builtin_convertvector(v, bf16x2_t); return __builtin_bit_cast(unsigned, b); }
; __device__ __forceinline__ void phase_rowpass(const Ctx& p, const float* F, int base_is_x, float alpha, const float* gpost, const float* gnext, bf16_t* XN, const float* PART, int nsplit) {
;     ...
;         for (int j = 0; j < 4; ++j) { b[j] = b[j] + f[j] * rs * gp[j]; s2 += (b[j].x * b[j].x + b[j].y * b[j].y) + (b[j].z * b[j].z + b[j].w * b[j].w);
;             ((f32x4*)(H + (size_t)m * DM))[lane + 64 * j] = b[j]; }
;         if (gnext) {
;             const float r2 = 1.f / sqrtf(wave_sum_fast(s2) * (1.f / DM) + EPS);
;             u32x2* o8 = (u32x2*)(XN + (size_t)m * DM) + lane;
; #pragma unroll
;             for (int j = 0; j < 4; ++j) { u32x2 w; w.x = pk2(b[j].x * r2 * gn[j].x, b[j].y * r2 * gn[j].y); w.y = pk2(b[j].z * r2 * gn[j].z, b[j].w * r2 * gn[j].w); o8[64 * j] = w; }
;         }
	global_store_dwordx4 v144, v[24:27], s[40:41] offset:2048
	global_store_dwordx4 v144, v[28:31], s[40:41] offset:3072
	v_mul_f32_e32 v96, v17, v17
	v_mul_f32_e32 v98, v19, v19
	v_fmac_f32_e32 v96, v16, v16
	v_fmac_f32_e32 v98, v18, v18
	v_add_f32_e32 v96, v96, v98
	v_mul_f32_e32 v97, v21, v21
	v_mul_f32_e32 v98, v23, v23
	v_fmac_f32_e32 v97, v20, v20
	v_fmac_f32_e32 v98, v22, v22
	v_add_f32_e32 v97, v97, v98
	v_add_f32_e32 v96, v97, v96
	v_mul_f32_e32 v97, v25, v25
	v_mul_f32_e32 v98, v27, v27
	v_fmac_f32_e32 v97, v24, v24
	v_fmac_f32_e32 v98, v26, v26
	v_add_f32_e32 v97, v97, v98
	v_add_f32_e32 v96, v97, v96
	v_mul_f32_e32 v97, v29, v29
	v_mul_f32_e32 v98, v31, v31
	v_fmac_f32_e32 v97, v28, v28
	v_fmac_f32_e32 v98, v30, v30
	v_add_f32_e32 v97, v97, v98
	v_add_f32_e32 v96, v97, v96
	s_nop 1
	v_add_f32_dpp v96, v96, v96 quad_perm:[1,0,3,2] row_mask:0xf bank_mask:0xf bound_ctrl:1
	s_nop 1
	v_add_f32_dpp v96, v96, v96 quad_perm:[2,3,0,1] row_mask:0xf bank_mask:0xf bound_ctrl:1
	s_nop 1
	v_add_f32_dpp v96, v96, v96 row_half_mirror row_mask:0xf bank_mask:0xf bound_ctrl:1
	s_nop 1
	v_add_f32_dpp v96, v96, v96 row_mirror row_mask:0xf bank_mask:0xf bound_ctrl:1
	v_mov_b32_e32 v97, v96
	s_nop 1
	v_permlane16_swap_b32_e32 v96, v97
	v_add_f32_e32 v96, v96, v97
	v_mov_b32_e32 v97, v96
	s_nop 1
	v_permlane32_swap_b32_e32 v96, v97
	v_add_f32_e32 v96, v96, v97
	v_fmamk_f32 v96, v96, 0x3a800000, v146
	v_mul_f32_e32 v97, 0x4f800000, v96
	v_cmp_gt_f32_e32 vcc, s33, v96
	s_nop 1
	v_cndmask_b32_e32 v96, v96, v97, vcc
	v_sqrt_f32_e32 v97, v96
	s_nop 0
	v_add_u32_e32 v98, -1, v97
	v_fma_f32 v99, -v98, v97, v96
	v_cmp_ge_f32_e64 s[4:5], 0, v99
	v_add_u32_e32 v99, 1, v97
	s_nop 0
	v_cndmask_b32_e64 v98, v97, v98, s[4:5]
	v_fma_f32 v97, -v99, v97, v96
	v_cmp_lt_f32_e64 s[4:5], 0, v97
	s_nop 1
	v_cndmask_b32_e64 v97, v98, v99, s[4:5]
	v_mul_f32_e32 v98, 0x37800000, v97
	v_cndmask_b32_e32 v97, v97, v98, vcc
	v_cmp_class_f32_e32 vcc, v96, v147
	s_nop 1
	v_cndmask_b32_e32 v96, v97, v96, vcc
	v_div_scale_f32 v97, s[4:5], v96, v96, 1.0
	v_rcp_f32_e32 v98, v97
	s_nop 0
	v_fma_f32 v99, -v97, v98, 1.0
	v_fmac_f32_e32 v98, v99, v98
	v_div_scale_f32 v99, vcc, 1.0, v96, 1.0
	v_mul_f32_e32 v100, v99, v98
	v_fma_f32 v101, -v97, v100, v99
	v_fmac_f32_e32 v100, v101, v98
	v_fma_f32 v97, -v97, v100, v99
	v_div_fmas_f32 v97, v97, v98, v100
	v_div_fixup_f32 v96, v97, v96, 1.0
	v_mul_f32_e32 v0, v16, v96
	v_mul_f32_e32 v1, v17, v96
	v_mul_f32_e32 v2, v18, v96
	v_mul_f32_e32 v3, v19, v96
	v_mul_f32_e32 v4, v20, v96
	v_mul_f32_e32 v5, v21, v96
	v_mul_f32_e32 v6, v22, v96
	v_mul_f32_e32 v7, v23, v96
	v_mul_f32_e32 v8, v24, v96
	v_mul_f32_e32 v9, v25, v96
	v_mul_f32_e32 v10, v26, v96
	v_mul_f32_e32 v11, v27, v96
	v_mul_f32_e32 v12, v28, v96
	v_mul_f32_e32 v13, v29, v96
	v_mul_f32_e32 v14, v30, v96
	v_mul_f32_e32 v15, v31, v96
	v_mul_f32_e32 v0, v128, v0
	v_mul_f32_e32 v1, v129, v1
	v_mul_f32_e32 v2, v130, v2
	v_mul_f32_e32 v3, v131, v3
	v_mul_f32_e32 v4, v132, v4
	v_mul_f32_e32 v5, v133, v5
	v_mul_f32_e32 v6, v134, v6
	v_mul_f32_e32 v7, v135, v7
	v_mul_f32_e32 v8, v136, v8
	v_mul_f32_e32 v9, v137, v9
	v_mul_f32_e32 v10, v138, v10
	v_mul_f32_e32 v11, v139, v11
	v_mul_f32_e32 v12, v140, v12
	v_mul_f32_e32 v13, v141, v13
	v_mul_f32_e32 v14, v142, v14
	v_mul_f32_e32 v15, v143, v15
	v_cvt_pk_bf16_f32 v148, v0, v1
	v_cvt_pk_bf16_f32 v149, v2, v3
	global_store_dwordx2 v145, v[148:149], s[42:43] offset:0
	v_cvt_pk_bf16_f32 v150, v4, v5
	v_cvt_pk_bf16_f32 v151, v6, v7
	global_store_dwordx2 v145, v[150:151], s[42:43] offset:512
	v_cvt_pk_bf16_f32 v152, v8, v9
	v_cvt_pk_bf16_f32 v153, v10, v11
	global_store_dwordx2 v145, v[152:153], s[42:43] offset:1024
	v_cvt_pk_bf16_f32 v154, v12, v13
	v_cvt_pk_bf16_f32 v155, v14, v15
	global_store_dwordx2 v145, v[154:155], s[42:43] offset:1536
	s_add_u32 s40, s40, 0x1000
	s_addc_u32 s41, s41, 0
	s_add_u32 s42, s42, 0x800
	s_addc_u32 s43, s43, 0
	global_load_dwordx4 v[0:3], v144, s[24:25] offset:0
	global_load_dwordx4 v[4:7], v144, s[24:25] offset:1024
	global_load_dwordx4 v[8:11], v144, s[24:25] offset:2048
	global_load_dwordx4 v[12:15], v144, s[24:25] offset:3072
	global_load_dwordx4 v[16:19], v144, s[26:27] offset:0
	global_load_dwordx4 v[20:23], v144, s[26:27] offset:1024
	global_load_dwordx4 v[24:27], v144, s[26:27] offset:2048
	global_load_dwordx4 v[28:31], v144, s[26:27] offset:3072
	s_add_u32 s24, s24, 0x1000
	s_addc_u32 s25, s25, 0
	s_add_u32 s26, s26, 0x1000
	s_addc_u32 s27, s27, 0
	s_waitcnt vmcnt(24)
; __device__ __forceinline__ unsigned pk2(float lo, float hi) { f32x2 v = {lo, hi}; bf16x2_t b = __builtin_convertvector(v, bf16x2_t); return __builtin_bit_cast(unsigned, b); }
; __device__ __forceinline__ void phase_rowpass(const Ctx& p, const float* F, int base_is_x, float alpha, const float* gpost, const float* gnext, bf16_t* XN, const float* PART, int nsplit) {
;     ...
;         float s = 0.f;
; #pragma unroll
;         for (int j = 0; j < 4; ++j) s += (f[j].x * f[j].x + f[j].y * f[j].y) + (f[j].z * f[j].z + f[j].w * f[j].w);
;         const float rs = alpha / sqrtf(wave_sum_fast(s) * (1.f / DM) + EPS);
;         float s2 = 0.f;
; #pragma unroll
;         for (int j = 0; j < 4; ++j) { b[j] = b[j] + f[j] * rs * gp[j]; s2 += (b[j].x * b[j].x + b[j].y * b[j].y) + (b[j].z * b[j].z + b[j].w * b[j].w);
;             ((f32x4*)(H + (size_t)m * DM))[lane + 64 * j] = b[j]; }
;         if (gnext) {
;             const float r2 = 1.f / sqrtf(wave_sum_fast(s2) * (1.f / DM) + EPS);
;             u32x2* o8 = (u32x2*)(XN + (size_t)m * DM) + lane;
; #pragma unroll
;             for (int j = 0; j < 4; ++j) { u32x2 w; w.x = pk2(b[j].x * r2 * gn[j].x, b[j].y * r2 * gn[j].y); w.y = pk2(b[j].z * r2 * gn[j].z, b[j].w * r2 * gn[j].w); o8[64 * j] = w; }
;         }
	v_mul_f32_e32 v96, v33, v33
	v_mul_f32_e32 v98, v35, v35
	v_fmac_f32_e32 v96, v32, v32
	v_fmac_f32_e32 v98, v34, v34
	v_add_f32_e32 v96, v96, v98
	v_mul_f32_e32 v97, v37, v37
	v_mul_f32_e32 v98, v39, v39
	v_fmac_f32_e32 v97, v36, v36
	v_fmac_f32_e32 v98, v38, v38
	v_add_f32_e32 v97, v97, v98
	v_add_f32_e32 v96, v97, v96
	v_mul_f32_e32 v97, v41, v41
	v_mul_f32_e32 v98, v43, v43
	v_fmac_f32_e32 v97, v40, v40
	v_fmac_f32_e32 v98, v42, v42
	v_add_f32_e32 v97, v97, v98
	v_add_f32_e32 v96, v97, v96
	v_mul_f32_e32 v97, v45, v45
	v_mul_f32_e32 v98, v47, v47
	v_fmac_f32_e32 v97, v44, v44
	v_fmac_f32_e32 v98, v46, v46
	v_add_f32_e32 v97, v97, v98
	v_add_f32_e32 v96, v97, v96
	s_nop 1
	v_add_f32_dpp v96, v96, v96 quad_perm:[1,0,3,2] row_mask:0xf bank_mask:0xf bound_ctrl:1
	s_nop 1
	v_add_f32_dpp v96, v96, v96 quad_perm:[2,3,0,1] row_mask:0xf bank_mask:0xf bound_ctrl:1
	s_nop 1
	v_add_f32_dpp v96, v96, v96 row_half_mirror row_mask:0xf bank_mask:0xf bound_ctrl:1
	s_nop 1
	v_add_f32_dpp v96, v96, v96 row_mirror row_mask:0xf bank_mask:0xf bound_ctrl:1
	v_mov_b32_e32 v97, v96
	s_nop 1
	v_permlane16_swap_b32_e32 v96, v97
	v_add_f32_e32 v96, v96, v97
	v_mov_b32_e32 v97, v96
	s_nop 1
	v_permlane32_swap_b32_e32 v96, v97
	v_add_f32_e32 v96, v96, v97
	v_fmamk_f32 v96, v96, 0x3a800000, v146
	v_mul_f32_e32 v97, 0x4f800000, v96
	v_cmp_gt_f32_e32 vcc, s33, v96
	s_nop 1
	v_cndmask_b32_e32 v96, v96, v97, vcc
	v_sqrt_f32_e32 v97, v96
	s_nop 0
	v_add_u32_e32 v98, -1, v97
	v_fma_f32 v99, -v98, v97, v96
	v_cmp_ge_f32_e64 s[4:5], 0, v99
	v_add_u32_e32 v99, 1, v97
	s_nop 0
	v_cndmask_b32_e64 v98, v97, v98, s[4:5]
	v_fma_f32 v97, -v99, v97, v96
	v_cmp_lt_f32_e64 s[4:5], 0, v97
	s_nop 1
	v_cndmask_b32_e64 v97, v98, v99, s[4:5]
	v_mul_f32_e32 v98, 0x37800000, v97
	v_cndmask_b32_e32 v97, v97, v98, vcc
	v_cmp_class_f32_e32 vcc, v96, v147
	s_nop 1
	v_cndmask_b32_e32 v96, v97, v96, vcc
	v_div_scale_f32 v97, s[4:5], v96, v96, 0.5
	v_rcp_f32_e32 v98, v97
	s_nop 0
	v_fma_f32 v99, -v97, v98, 1.0
	v_fmac_f32_e32 v98, v99, v98
	v_div_scale_f32 v99, vcc, 0.5, v96, 0.5
	v_mul_f32_e32 v100, v99, v98
	v_fma_f32 v101, -v97, v100, v99
	v_fmac_f32_e32 v100, v101, v98
	v_fma_f32 v97, -v97, v100, v99
	v_div_fmas_f32 v97, v97, v98, v100
	v_div_fixup_f32 v96, v97, v96, 0.5
	v_mul_f32_e32 v32, v32, v96
	v_mul_f32_e32 v33, v33, v96
	v_mul_f32_e32 v34, v34, v96
	v_mul_f32_e32 v35, v35, v96
	v_mul_f32_e32 v36, v36, v96
	v_mul_f32_e32 v37, v37, v96
	v_mul_f32_e32 v38, v38, v96
	v_mul_f32_e32 v39, v39, v96
	v_mul_f32_e32 v40, v40, v96
	v_mul_f32_e32 v41, v41, v96
	v_mul_f32_e32 v42, v42, v96
	v_mul_f32_e32 v43, v43, v96
	v_mul_f32_e32 v44, v44, v96
	v_mul_f32_e32 v45, v45, v96
	v_mul_f32_e32 v46, v46, v96
	v_mul_f32_e32 v47, v47, v96
	v_fmac_f32_e32 v48, v112, v32
	v_fmac_f32_e32 v49, v113, v33
	v_fmac_f32_e32 v50, v114, v34
	v_fmac_f32_e32 v51, v115, v35
	v_fmac_f32_e32 v52, v116, v36
	v_fmac_f32_e32 v53, v117, v37
	v_fmac_f32_e32 v54, v118, v38
	v_fmac_f32_e32 v55, v119, v39
	v_fmac_f32_e32 v56, v120, v40
	v_fmac_f32_e32 v57, v121, v41
	v_fmac_f32_e32 v58, v122, v42
	v_fmac_f32_e32 v59, v123, v43
	v_fmac_f32_e32 v60, v124, v44
	v_fmac_f32_e32 v61, v125, v45
	v_fmac_f32_e32 v62, v126, v46
	v_fmac_f32_e32 v63, v127, v47
	global_store_dwordx4 v144, v[48:51], s[40:41] offset:0
	global_store_dwordx4 v144, v[52:55], s[40:41] offset:1024
	global_store_dwordx4 v144, v[56:59], s[40:41] offset:2048
	global_store_dwordx4 v144, v[60:63], s[40:41] offset:3072
	v_mul_f32_e32 v96, v49, v49
	v_mul_f32_e32 v98, v51, v51
	v_fmac_f32_e32 v96, v48, v48
	v_fmac_f32_e32 v98, v50, v50
	v_add_f32_e32 v96, v96, v98
	v_mul_f32_e32 v97, v53, v53
	v_mul_f32_e32 v98, v55, v55
	v_fmac_f32_e32 v97, v52, v52
	v_fmac_f32_e32 v98, v54, v54
	v_add_f32_e32 v97, v97, v98
	v_add_f32_e32 v96, v97, v96
	v_mul_f32_e32 v97, v57, v57
	v_mul_f32_e32 v98, v59, v59
	v_fmac_f32_e32 v97, v56, v56
	v_fmac_f32_e32 v98, v58, v58
	v_add_f32_e32 v97, v97, v98
	v_add_f32_e32 v96, v97, v96
	v_mul_f32_e32 v97, v61, v61
	v_mul_f32_e32 v98, v63, v63
	v_fmac_f32_e32 v97, v60, v60
	v_fmac_f32_e32 v98, v62, v62
	v_add_f32_e32 v97, v97, v98
	v_add_f32_e32 v96, v97, v96
	s_nop 1
	v_add_f32_dpp v96, v96, v96 quad_perm:[1,0,3,2] row_mask:0xf bank_mask:0xf bound_ctrl:1
	s_nop 1
	v_add_f32_dpp v96, v96, v96 quad_perm:[2,3,0,1] row_mask:0xf bank_mask:0xf bound_ctrl:1
	s_nop 1
	v_add_f32_dpp v96, v96, v96 row_half_mirror row_mask:0xf bank_mask:0xf bound_ctrl:1
	s_nop 1
	v_add_f32_dpp v96, v96, v96 row_mirror row_mask:0xf bank_mask:0xf bound_ctrl:1
	v_mov_b32_e32 v97, v96
	s_nop 1
	v_permlane16_swap_b32_e32 v96, v97
	v_add_f32_e32 v96, v96, v97
	v_mov_b32_e32 v97, v96
	s_nop 1
	v_permlane32_swap_b32_e32 v96, v97
	v_add_f32_e32 v96, v96, v97
	v_fmamk_f32 v96, v96, 0x3a800000, v146
	v_mul_f32_e32 v97, 0x4f800000, v96
	v_cmp_gt_f32_e32 vcc, s33, v96
	s_nop 1
	v_cndmask_b32_e32 v96, v96, v97, vcc
	v_sqrt_f32_e32 v97, v96
	s_nop 0
	v_add_u32_e32 v98, -1, v97
	v_fma_f32 v99, -v98, v97, v96
	v_cmp_ge_f32_e64 s[4:5], 0, v99
	v_add_u32_e32 v99, 1, v97
	s_nop 0
	v_cndmask_b32_e64 v98, v97, v98, s[4:5]
	v_fma_f32 v97, -v99, v97, v96
	v_cmp_lt_f32_e64 s[4:5], 0, v97
	s_nop 1
	v_cndmask_b32_e64 v97, v98, v99, s[4:5]
	v_mul_f32_e32 v98, 0x37800000, v97
	v_cndmask_b32_e32 v97, v97, v98, vcc
	v_cmp_class_f32_e32 vcc, v96, v147
	s_nop 1
	v_cndmask_b32_e32 v96, v97, v96, vcc
	v_div_scale_f32 v97, s[4:5], v96, v96, 1.0
	v_rcp_f32_e32 v98, v97
	s_nop 0
	v_fma_f32 v99, -v97, v98, 1.0
	v_fmac_f32_e32 v98, v99, v98
	v_div_scale_f32 v99, vcc, 1.0, v96, 1.0
	v_mul_f32_e32 v100, v99, v98
	v_fma_f32 v101, -v97, v100, v99
	v_fmac_f32_e32 v100, v101, v98
	v_fma_f32 v97, -v97, v100, v99
; __device__ __forceinline__ unsigned pk2(float lo, float hi) { f32x2 v = {lo, hi}; bf16x2_t b = __builtin_convertvector(v, bf16x2_t); return __builtin_bit_cast(unsigned, b); }
; __device__ __forceinline__ void phase_rowpass(const Ctx& p, const float* F, int base_is_x, float alpha, const float* gpost, const float* gnext, bf16_t* XN, const float* PART, int nsplit) {
;     ...
;         float s = 0.f;
; #pragma unroll
;         for (int j = 0; j < 4; ++j) s += (f[j].x * f[j].x + f[j].y * f[j].y) + (f[j].z * f[j].z + f[j].w * f[j].w);
;         const float rs = alpha / sqrtf(wave_sum_fast(s) * (1.f / DM) + EPS);
;         float s2 = 0.f;
; #pragma unroll
;         for (int j = 0; j < 4; ++j) { b[j] = b[j] + f[j] * rs * gp[j]; s2 += (b[j].x * b[j].x + b[j].y * b[j].y) + (b[j].z * b[j].z + b[j].w * b[j].w);
;             ((f32x4*)(H + (size_t)m * DM))[lane + 64 * j] = b[j]; }
;         if (gnext) {
;             const float r2 = 1.f / sqrtf(wave_sum_fast(s2) * (1.f / DM) + EPS);
;             u32x2* o8 = (u32x2*)(XN + (size_t)m * DM) + lane;
; #pragma unroll
;             for (int j = 0; j < 4; ++j) { u32x2 w; w.x = pk2(b[j].x * r2 * gn[j].x, b[j].y * r2 * gn[j].y); w.y = pk2(b[j].z * r2 * gn[j].z, b[j].w * r2 * gn[j].w); o8[64 * j] = w; }
;         }
	v_div_fmas_f32 v97, v97, v98, v100
	v_div_fixup_f32 v96, v97, v96, 1.0
	v_mul_f32_e32 v32, v48, v96
	v_mul_f32_e32 v33, v49, v96
	v_mul_f32_e32 v34, v50, v96
	v_mul_f32_e32 v35, v51, v96
	v_mul_f32_e32 v36, v52, v96
	v_mul_f32_e32 v37, v53, v96
	v_mul_f32_e32 v38, v54, v96
	v_mul_f32_e32 v39, v55, v96
	v_mul_f32_e32 v40, v56, v96
	v_mul_f32_e32 v41, v57, v96
	v_mul_f32_e32 v42, v58, v96
	v_mul_f32_e32 v43, v59, v96
	v_mul_f32_e32 v44, v60, v96
	v_mul_f32_e32 v45, v61, v96
	v_mul_f32_e32 v46, v62, v96
	v_mul_f32_e32 v47, v63, v96
	v_mul_f32_e32 v32, v128, v32
	v_mul_f32_e32 v33, v129, v33
	v_mul_f32_e32 v34, v130, v34
	v_mul_f32_e32 v35, v131, v35
	v_mul_f32_e32 v36, v132, v36
	v_mul_f32_e32 v37, v133, v37
	v_mul_f32_e32 v38, v134, v38
	v_mul_f32_e32 v39, v135, v39
	v_mul_f32_e32 v40, v136, v40
	v_mul_f32_e32 v41, v137, v41
	v_mul_f32_e32 v42, v138, v42
	v_mul_f32_e32 v43, v139, v43
	v_mul_f32_e32 v44, v140, v44
	v_mul_f32_e32 v45, v141, v45
	v_mul_f32_e32 v46, v142, v46
	v_mul_f32_e32 v47, v143, v47
	v_cvt_pk_bf16_f32 v148, v32, v33
	v_cvt_pk_bf16_f32 v149, v34, v35
	global_store_dwordx2 v145, v[148:149], s[42:43] offset:0
	v_cvt_pk_bf16_f32 v150, v36, v37
	v_cvt_pk_bf16_f32 v151, v38, v39
	global_store_dwordx2 v145, v[150:151], s[42:43] offset:512
	v_cvt_pk_bf16_f32 v152, v40, v41
	v_cvt_pk_bf16_f32 v153, v42, v43
	global_store_dwordx2 v145, v[152:153], s[42:43] offset:1024
	v_cvt_pk_bf16_f32 v154, v44, v45
	v_cvt_pk_bf16_f32 v155, v46, v47
	global_store_dwordx2 v145, v[154:155], s[42:43] offset:1536
	s_add_u32 s40, s40, 0x1000
	s_addc_u32 s41, s41, 0
	s_add_u32 s42, s42, 0x800
	s_addc_u32 s43, s43, 0
	global_load_dwordx4 v[32:35], v144, s[24:25] offset:0
	global_load_dwordx4 v[36:39], v144, s[24:25] offset:1024
	global_load_dwordx4 v[40:43], v144, s[24:25] offset:2048
	global_load_dwordx4 v[44:47], v144, s[24:25] offset:3072
	global_load_dwordx4 v[48:51], v144, s[26:27] offset:0
	global_load_dwordx4 v[52:55], v144, s[26:27] offset:1024
	global_load_dwordx4 v[56:59], v144, s[26:27] offset:2048
	global_load_dwordx4 v[60:63], v144, s[26:27] offset:3072
	s_add_u32 s24, s24, 0x1000
	s_addc_u32 s25, s25, 0
	s_add_u32 s26, s26, 0x1000
	s_addc_u32 s27, s27, 0
	s_waitcnt vmcnt(32)
	v_mul_f32_e32 v96, v65, v65
	v_mul_f32_e32 v98, v67, v67
	v_fmac_f32_e32 v96, v64, v64
	v_fmac_f32_e32 v98, v66, v66
	v_add_f32_e32 v96, v96, v98
	v_mul_f32_e32 v97, v69, v69
	v_mul_f32_e32 v98, v71, v71
	v_fmac_f32_e32 v97, v68, v68
	v_fmac_f32_e32 v98, v70, v70
	v_add_f32_e32 v97, v97, v98
	v_add_f32_e32 v96, v97, v96
	v_mul_f32_e32 v97, v73, v73
	v_mul_f32_e32 v98, v75, v75
	v_fmac_f32_e32 v97, v72, v72
	v_fmac_f32_e32 v98, v74, v74
	v_add_f32_e32 v97, v97, v98
	v_add_f32_e32 v96, v97, v96
	v_mul_f32_e32 v97, v77, v77
	v_mul_f32_e32 v98, v79, v79
	v_fmac_f32_e32 v97, v76, v76
	v_fmac_f32_e32 v98, v78, v78
	v_add_f32_e32 v97, v97, v98
	v_add_f32_e32 v96, v97, v96
	s_nop 1
	v_add_f32_dpp v96, v96, v96 quad_perm:[1,0,3,2] row_mask:0xf bank_mask:0xf bound_ctrl:1
	s_nop 1
	v_add_f32_dpp v96, v96, v96 quad_perm:[2,3,0,1] row_mask:0xf bank_mask:0xf bound_ctrl:1
	s_nop 1
	v_add_f32_dpp v96, v96, v96 row_half_mirror row_mask:0xf bank_mask:0xf bound_ctrl:1
	s_nop 1
	v_add_f32_dpp v96, v96, v96 row_mirror row_mask:0xf bank_mask:0xf bound_ctrl:1
	v_mov_b32_e32 v97, v96
	s_nop 1
	v_permlane16_swap_b32_e32 v96, v97
	v_add_f32_e32 v96, v96, v97
	v_mov_b32_e32 v97, v96
	s_nop 1
	v_permlane32_swap_b32_e32 v96, v97
	v_add_f32_e32 v96, v96, v97
	v_fmamk_f32 v96, v96, 0x3a800000, v146
	v_mul_f32_e32 v97, 0x4f800000, v96
	v_cmp_gt_f32_e32 vcc, s33, v96
	s_nop 1
	v_cndmask_b32_e32 v96, v96, v97, vcc
	v_sqrt_f32_e32 v97, v96
	s_nop 0
	v_add_u32_e32 v98, -1, v97
	v_fma_f32 v99, -v98, v97, v96
	v_cmp_ge_f32_e64 s[4:5], 0, v99
	v_add_u32_e32 v99, 1, v97
	s_nop 0
	v_cndmask_b32_e64 v98, v97, v98, s[4:5]
	v_fma_f32 v97, -v99, v97, v96
	v_cmp_lt_f32_e64 s[4:5], 0, v97
	s_nop 1
	v_cndmask_b32_e64 v97, v98, v99, s[4:5]
	v_mul_f32_e32 v98, 0x37800000, v97
	v_cndmask_b32_e32 v97, v97, v98, vcc
	v_cmp_class_f32_e32 vcc, v96, v147
	s_nop 1
	v_cndmask_b32_e32 v96, v97, v96, vcc
	v_div_scale_f32 v97, s[4:5], v96, v96, 0.5
	v_rcp_f32_e32 v98, v97
	s_nop 0
	v_fma_f32 v99, -v97, v98, 1.0
	v_fmac_f32_e32 v98, v99, v98
	v_div_scale_f32 v99, vcc, 0.5, v96, 0.5
	v_mul_f32_e32 v100, v99, v98
	v_fma_f32 v101, -v97, v100, v99
	v_fmac_f32_e32 v100, v101, v98
	v_fma_f32 v97, -v97, v100, v99
	v_div_fmas_f32 v97, v97, v98, v100
	v_div_fixup_f32 v96, v97, v96, 0.5
	v_mul_f32_e32 v64, v64, v96
	v_mul_f32_e32 v65, v65, v96
	v_mul_f32_e32 v66, v66, v96
	v_mul_f32_e32 v67, v67, v96
	v_mul_f32_e32 v68, v68, v96
	v_mul_f32_e32 v69, v69, v96
	v_mul_f32_e32 v70, v70, v96
	v_mul_f32_e32 v71, v71, v96
	v_mul_f32_e32 v72, v72, v96
	v_mul_f32_e32 v73, v73, v96
	v_mul_f32_e32 v74, v74, v96
	v_mul_f32_e32 v75, v75, v96
	v_mul_f32_e32 v76, v76, v96
	v_mul_f32_e32 v77, v77, v96
	v_mul_f32_e32 v78, v78, v96
	v_mul_f32_e32 v79, v79, v96
	v_fmac_f32_e32 v80, v112, v64
	v_fmac_f32_e32 v81, v113, v65
	v_fmac_f32_e32 v82, v114, v66
	v_fmac_f32_e32 v83, v115, v67
	v_fmac_f32_e32 v84, v116, v68
	v_fmac_f32_e32 v85, v117, v69
	v_fmac_f32_e32 v86, v118, v70
	v_fmac_f32_e32 v87, v119, v71
	v_fmac_f32_e32 v88, v120, v72
	v_fmac_f32_e32 v89, v121, v73
	v_fmac_f32_e32 v90, v122, v74
	v_fmac_f32_e32 v91, v123, v75
	v_fmac_f32_e32 v92, v124, v76
	v_fmac_f32_e32 v93, v125, v77
	v_fmac_f32_e32 v94, v126, v78
	v_fmac_f32_e32 v95, v127, v79
	global_store_dwordx4 v144, v[80:83], s[40:41] offset:0
	global_store_dwordx4 v144, v[84:87], s[40:41] offset:1024
	global_store_dwordx4 v144, v[88:91], s[40:41] offset:2048
	global_store_dwordx4 v144, v[92:95], s[40:41] offset:3072
; __device__ __forceinline__ unsigned pk2(float lo, float hi) { f32x2 v = {lo, hi}; bf16x2_t b = __builtin_convertvector(v, bf16x2_t); return __builtin_bit_cast(unsigned, b); }
; __device__ __forceinline__ void phase_rowpass(const Ctx& p, const float* F, int base_is_x, float alpha, const float* gpost, const float* gnext, bf16_t* XN, const float* PART, int nsplit) {
;     ...
;         for (int j = 0; j < 4; ++j) { b[j] = b[j] + f[j] * rs * gp[j]; s2 += (b[j].x * b[j].x + b[j].y * b[j].y) + (b[j].z * b[j].z + b[j].w * b[j].w);
;             ((f32x4*)(H + (size_t)m * DM))[lane + 64 * j] = b[j]; }
;         if (gnext) {
;             const float r2 = 1.f / sqrtf(wave_sum_fast(s2) * (1.f / DM) + EPS);
;             u32x2* o8 = (u32x2*)(XN + (size_t)m * DM) + lane;
; #pragma unroll
;             for (int j = 0; j < 4; ++j) { u32x2 w; w.x = pk2(b[j].x * r2 * gn[j].x, b[j].y * r2 * gn[j].y); w.y = pk2(b[j].z * r2 * gn[j].z, b[j].w * r2 * gn[j].w); o8[64 * j] = w; }
;         }
;         if (more) {
; #pragma unroll
;             for (int j = 0; j < 4; ++j) { f[j] = f2[j]; b[j] = b2[j]; } }
	v_mul_f32_e32 v96, v81, v81
	v_mul_f32_e32 v98, v83, v83
	v_fmac_f32_e32 v96, v80, v80
	v_fmac_f32_e32 v98, v82, v82
	v_add_f32_e32 v96, v96, v98
	v_mul_f32_e32 v97, v85, v85
	v_mul_f32_e32 v98, v87, v87
	v_fmac_f32_e32 v97, v84, v84
	v_fmac_f32_e32 v98, v86, v86
	v_add_f32_e32 v97, v97, v98
	v_add_f32_e32 v96, v97, v96
	v_mul_f32_e32 v97, v89, v89
	v_mul_f32_e32 v98, v91, v91
	v_fmac_f32_e32 v97, v88, v88
	v_fmac_f32_e32 v98, v90, v90
	v_add_f32_e32 v97, v97, v98
	v_add_f32_e32 v96, v97, v96
	v_mul_f32_e32 v97, v93, v93
	v_mul_f32_e32 v98, v95, v95
	v_fmac_f32_e32 v97, v92, v92
	v_fmac_f32_e32 v98, v94, v94
	v_add_f32_e32 v97, v97, v98
	v_add_f32_e32 v96, v97, v96
	s_nop 1
	v_add_f32_dpp v96, v96, v96 quad_perm:[1,0,3,2] row_mask:0xf bank_mask:0xf bound_ctrl:1
	s_nop 1
	v_add_f32_dpp v96, v96, v96 quad_perm:[2,3,0,1] row_mask:0xf bank_mask:0xf bound_ctrl:1
	s_nop 1
	v_add_f32_dpp v96, v96, v96 row_half_mirror row_mask:0xf bank_mask:0xf bound_ctrl:1
	s_nop 1
	v_add_f32_dpp v96, v96, v96 row_mirror row_mask:0xf bank_mask:0xf bound_ctrl:1
	v_mov_b32_e32 v97, v96
	s_nop 1
	v_permlane16_swap_b32_e32 v96, v97
	v_add_f32_e32 v96, v96, v97
	v_mov_b32_e32 v97, v96
	s_nop 1
	v_permlane32_swap_b32_e32 v96, v97
	v_add_f32_e32 v96, v96, v97
	v_fmamk_f32 v96, v96, 0x3a800000, v146
	v_mul_f32_e32 v97, 0x4f800000, v96
	v_cmp_gt_f32_e32 vcc, s33, v96
	s_nop 1
	v_cndmask_b32_e32 v96, v96, v97, vcc
	v_sqrt_f32_e32 v97, v96
	s_nop 0
	v_add_u32_e32 v98, -1, v97
	v_fma_f32 v99, -v98, v97, v96
	v_cmp_ge_f32_e64 s[4:5], 0, v99
	v_add_u32_e32 v99, 1, v97
	s_nop 0
	v_cndmask_b32_e64 v98, v97, v98, s[4:5]
	v_fma_f32 v97, -v99, v97, v96
	v_cmp_lt_f32_e64 s[4:5], 0, v97
	s_nop 1
	v_cndmask_b32_e64 v97, v98, v99, s[4:5]
	v_mul_f32_e32 v98, 0x37800000, v97
	v_cndmask_b32_e32 v97, v97, v98, vcc
	v_cmp_class_f32_e32 vcc, v96, v147
	s_nop 1
	v_cndmask_b32_e32 v96, v97, v96, vcc
	v_div_scale_f32 v97, s[4:5], v96, v96, 1.0
	v_rcp_f32_e32 v98, v97
	s_nop 0
	v_fma_f32 v99, -v97, v98, 1.0
	v_fmac_f32_e32 v98, v99, v98
	v_div_scale_f32 v99, vcc, 1.0, v96, 1.0
	v_mul_f32_e32 v100, v99, v98
	v_fma_f32 v101, -v97, v100, v99
	v_fmac_f32_e32 v100, v101, v98
	v_fma_f32 v97, -v97, v100, v99
	v_div_fmas_f32 v97, v97, v98, v100
	v_div_fixup_f32 v96, v97, v96, 1.0
	v_mul_f32_e32 v64, v80, v96
	v_mul_f32_e32 v65, v81, v96
	v_mul_f32_e32 v66, v82, v96
	v_mul_f32_e32 v67, v83, v96
	v_mul_f32_e32 v68, v84, v96
	v_mul_f32_e32 v69, v85, v96
	v_mul_f32_e32 v70, v86, v96
	v_mul_f32_e32 v71, v87, v96
	v_mul_f32_e32 v72, v88, v96
	v_mul_f32_e32 v73, v89, v96
	v_mul_f32_e32 v74, v90, v96
	v_mul_f32_e32 v75, v91, v96
	v_mul_f32_e32 v76, v92, v96
	v_mul_f32_e32 v77, v93, v96
	v_mul_f32_e32 v78, v94, v96
	v_mul_f32_e32 v79, v95, v96
	v_mul_f32_e32 v64, v128, v64
	v_mul_f32_e32 v65, v129, v65
	v_mul_f32_e32 v66, v130, v66
	v_mul_f32_e32 v67, v131, v67
	v_mul_f32_e32 v68, v132, v68
	v_mul_f32_e32 v69, v133, v69
	v_mul_f32_e32 v70, v134, v70
	v_mul_f32_e32 v71, v135, v71
	v_mul_f32_e32 v72, v136, v72
	v_mul_f32_e32 v73, v137, v73
	v_mul_f32_e32 v74, v138, v74
	v_mul_f32_e32 v75, v139, v75
	v_mul_f32_e32 v76, v140, v76
	v_mul_f32_e32 v77, v141, v77
	v_mul_f32_e32 v78, v142, v78
	v_mul_f32_e32 v79, v143, v79
	v_cvt_pk_bf16_f32 v148, v64, v65
	v_cvt_pk_bf16_f32 v149, v66, v67
	global_store_dwordx2 v145, v[148:149], s[42:43] offset:0
	v_cvt_pk_bf16_f32 v150, v68, v69
	v_cvt_pk_bf16_f32 v151, v70, v71
	global_store_dwordx2 v145, v[150:151], s[42:43] offset:512
	v_cvt_pk_bf16_f32 v152, v72, v73
	v_cvt_pk_bf16_f32 v153, v74, v75
	global_store_dwordx2 v145, v[152:153], s[42:43] offset:1024
	v_cvt_pk_bf16_f32 v154, v76, v77
	v_cvt_pk_bf16_f32 v155, v78, v79
	global_store_dwordx2 v145, v[154:155], s[42:43] offset:1536
	s_add_u32 s40, s40, 0x1000
	s_addc_u32 s41, s41, 0
	s_add_u32 s42, s42, 0x800
	s_addc_u32 s43, s43, 0
	global_load_dwordx4 v[64:67], v144, s[24:25] offset:0
	global_load_dwordx4 v[68:71], v144, s[24:25] offset:1024
	global_load_dwordx4 v[72:75], v144, s[24:25] offset:2048
	global_load_dwordx4 v[76:79], v144, s[24:25] offset:3072
	global_load_dwordx4 v[80:83], v144, s[26:27] offset:0
	global_load_dwordx4 v[84:87], v144, s[26:27] offset:1024
	global_load_dwordx4 v[88:91], v144, s[26:27] offset:2048
	global_load_dwordx4 v[92:95], v144, s[26:27] offset:3072
	s_add_u32 s24, s24, 0x1000
	s_addc_u32 s25, s25, 0
	s_add_u32 s26, s26, 0x1000
	s_addc_u32 s27, s27, 0
	s_waitcnt vmcnt(32)
; __device__ __forceinline__ void phase_rowpass(const Ctx& p, const float* F, int base_is_x, float alpha, const float* gpost, const float* gnext, bf16_t* XN, const float* PART, int nsplit) {
;     ...
;         float s = 0.f;
; #pragma unroll
;         for (int j = 0; j < 4; ++j) s += (f[j].x * f[j].x + f[j].y * f[j].y) + (f[j].z * f[j].z + f[j].w * f[j].w);
;         const float rs = alpha / sqrtf(wave_sum_fast(s) * (1.f / DM) + EPS);
;         float s2 = 0.f;
; #pragma unroll
;         for (int j = 0; j < 4; ++j) { b[j] = b[j] + f[j] * rs * gp[j]; s2 += (b[j].x * b[j].x + b[j].y * b[j].y) + (b[j].z * b[j].z + b[j].w * b[j].w);
;             ((f32x4*)(H + (size_t)m * DM))[lane + 64 * j] = b[j]; }
;         if (gnext) {
;             const float r2 = 1.f / sqrtf(wave_sum_fast(s2) * (1.f / DM) + EPS);
	v_mul_f32_e32 v96, v1, v1
	v_mul_f32_e32 v98, v3, v3
	v_fmac_f32_e32 v96, v0, v0
	v_fmac_f32_e32 v98, v2, v2
	v_add_f32_e32 v96, v96, v98
	v_mul_f32_e32 v97, v5, v5
	v_mul_f32_e32 v98, v7, v7
	v_fmac_f32_e32 v97, v4, v4
	v_fmac_f32_e32 v98, v6, v6
	v_add_f32_e32 v97, v97, v98
	v_add_f32_e32 v96, v97, v96
	v_mul_f32_e32 v97, v9, v9
	v_mul_f32_e32 v98, v11, v11
	v_fmac_f32_e32 v97, v8, v8
	v_fmac_f32_e32 v98, v10, v10
	v_add_f32_e32 v97, v97, v98
	v_add_f32_e32 v96, v97, v96
	v_mul_f32_e32 v97, v13, v13
	v_mul_f32_e32 v98, v15, v15
	v_fmac_f32_e32 v97, v12, v12
	v_fmac_f32_e32 v98, v14, v14
	v_add_f32_e32 v97, v97, v98
	v_add_f32_e32 v96, v97, v96
	s_nop 1
	v_add_f32_dpp v96, v96, v96 quad_perm:[1,0,3,2] row_mask:0xf bank_mask:0xf bound_ctrl:1
	s_nop 1
	v_add_f32_dpp v96, v96, v96 quad_perm:[2,3,0,1] row_mask:0xf bank_mask:0xf bound_ctrl:1
	s_nop 1
	v_add_f32_dpp v96, v96, v96 row_half_mirror row_mask:0xf bank_mask:0xf bound_ctrl:1
	s_nop 1
	v_add_f32_dpp v96, v96, v96 row_mirror row_mask:0xf bank_mask:0xf bound_ctrl:1
	v_mov_b32_e32 v97, v96
	s_nop 1
	v_permlane16_swap_b32_e32 v96, v97
	v_add_f32_e32 v96, v96, v97
	v_mov_b32_e32 v97, v96
	s_nop 1
	v_permlane32_swap_b32_e32 v96, v97
	v_add_f32_e32 v96, v96, v97
	v_fmamk_f32 v96, v96, 0x3a800000, v146
	v_mul_f32_e32 v97, 0x4f800000, v96
	v_cmp_gt_f32_e32 vcc, s33, v96
	s_nop 1
	v_cndmask_b32_e32 v96, v96, v97, vcc
	v_sqrt_f32_e32 v97, v96
	s_nop 0
	v_add_u32_e32 v98, -1, v97
	v_fma_f32 v99, -v98, v97, v96
	v_cmp_ge_f32_e64 s[4:5], 0, v99
	v_add_u32_e32 v99, 1, v97
	s_nop 0
	v_cndmask_b32_e64 v98, v97, v98, s[4:5]
	v_fma_f32 v97, -v99, v97, v96
	v_cmp_lt_f32_e64 s[4:5], 0, v97
	s_nop 1
	v_cndmask_b32_e64 v97, v98, v99, s[4:5]
	v_mul_f32_e32 v98, 0x37800000, v97
	v_cndmask_b32_e32 v97, v97, v98, vcc
	v_cmp_class_f32_e32 vcc, v96, v147
	s_nop 1
	v_cndmask_b32_e32 v96, v97, v96, vcc
	v_div_scale_f32 v97, s[4:5], v96, v96, 0.5
	v_rcp_f32_e32 v98, v97
	s_nop 0
	v_fma_f32 v99, -v97, v98, 1.0
	v_fmac_f32_e32 v98, v99, v98
	v_div_scale_f32 v99, vcc, 0.5, v96, 0.5
	v_mul_f32_e32 v100, v99, v98
	v_fma_f32 v101, -v97, v100, v99
	v_fmac_f32_e32 v100, v101, v98
	v_fma_f32 v97, -v97, v100, v99
	v_div_fmas_f32 v97, v97, v98, v100
	v_div_fixup_f32 v96, v97, v96, 0.5
	v_mul_f32_e32 v0, v0, v96
	v_mul_f32_e32 v1, v1, v96
	v_mul_f32_e32 v2, v2, v96
	v_mul_f32_e32 v3, v3, v96
	v_mul_f32_e32 v4, v4, v96
	v_mul_f32_e32 v5, v5, v96
	v_mul_f32_e32 v6, v6, v96
	v_mul_f32_e32 v7, v7, v96
	v_mul_f32_e32 v8, v8, v96
	v_mul_f32_e32 v9, v9, v96
	v_mul_f32_e32 v10, v10, v96
	v_mul_f32_e32 v11, v11, v96
	v_mul_f32_e32 v12, v12, v96
	v_mul_f32_e32 v13, v13, v96
	v_mul_f32_e32 v14, v14, v96
	v_mul_f32_e32 v15, v15, v96
	v_fmac_f32_e32 v16, v112, v0
	v_fmac_f32_e32 v17, v113, v1
	v_fmac_f32_e32 v18, v114, v2
	v_fmac_f32_e32 v19, v115, v3
	v_fmac_f32_e32 v20, v116, v4
	v_fmac_f32_e32 v21, v117, v5
	v_fmac_f32_e32 v22, v118, v6
	v_fmac_f32_e32 v23, v119, v7
	v_fmac_f32_e32 v24, v120, v8
	v_fmac_f32_e32 v25, v121, v9
	v_fmac_f32_e32 v26, v122, v10
	v_fmac_f32_e32 v27, v123, v11
	v_fmac_f32_e32 v28, v124, v12
	v_fmac_f32_e32 v29, v125, v13
	v_fmac_f32_e32 v30, v126, v14
	v_fmac_f32_e32 v31, v127, v15
	global_store_dwordx4 v144, v[16:19], s[40:41] offset:0
	global_store_dwordx4 v144, v[20:23], s[40:41] offset:1024
	global_store_dwordx4 v144, v[24:27], s[40:41] offset:2048
	global_store_dwordx4 v144, v[28:31], s[40:41] offset:3072
	v_mul_f32_e32 v96, v17, v17
	v_mul_f32_e32 v98, v19, v19
	v_fmac_f32_e32 v96, v16, v16
	v_fmac_f32_e32 v98, v18, v18
	v_add_f32_e32 v96, v96, v98
	v_mul_f32_e32 v97, v21, v21
	v_mul_f32_e32 v98, v23, v23
	v_fmac_f32_e32 v97, v20, v20
	v_fmac_f32_e32 v98, v22, v22
	v_add_f32_e32 v97, v97, v98
	v_add_f32_e32 v96, v97, v96
	v_mul_f32_e32 v97, v25, v25
	v_mul_f32_e32 v98, v27, v27
	v_fmac_f32_e32 v97, v24, v24
	v_fmac_f32_e32 v98, v26, v26
	v_add_f32_e32 v97, v97, v98
	v_add_f32_e32 v96, v97, v96
	v_mul_f32_e32 v97, v29, v29
	v_mul_f32_e32 v98, v31, v31
	v_fmac_f32_e32 v97, v28, v28
	v_fmac_f32_e32 v98, v30, v30
	v_add_f32_e32 v97, v97, v98
	v_add_f32_e32 v96, v97, v96
	s_nop 1
	v_add_f32_dpp v96, v96, v96 quad_perm:[1,0,3,2] row_mask:0xf bank_mask:0xf bound_ctrl:1
	s_nop 1
	v_add_f32_dpp v96, v96, v96 quad_perm:[2,3,0,1] row_mask:0xf bank_mask:0xf bound_ctrl:1
	s_nop 1
	v_add_f32_dpp v96, v96, v96 row_half_mirror row_mask:0xf bank_mask:0xf bound_ctrl:1
	s_nop 1
	v_add_f32_dpp v96, v96, v96 row_mirror row_mask:0xf bank_mask:0xf bound_ctrl:1
	v_mov_b32_e32 v97, v96
	s_nop 1
	v_permlane16_swap_b32_e32 v96, v97
	v_add_f32_e32 v96, v96, v97
	v_mov_b32_e32 v97, v96
	s_nop 1
	v_permlane32_swap_b32_e32 v96, v97
	v_add_f32_e32 v96, v96, v97
	v_fmamk_f32 v96, v96, 0x3a800000, v146
	v_mul_f32_e32 v97, 0x4f800000, v96
	v_cmp_gt_f32_e32 vcc, s33, v96
	s_nop 1
	v_cndmask_b32_e32 v96, v96, v97, vcc
	v_sqrt_f32_e32 v97, v96
	s_nop 0
	v_add_u32_e32 v98, -1, v97
	v_fma_f32 v99, -v98, v97, v96
	v_cmp_ge_f32_e64 s[4:5], 0, v99
	v_add_u32_e32 v99, 1, v97
	s_nop 0
	v_cndmask_b32_e64 v98, v97, v98, s[4:5]
	v_fma_f32 v97, -v99, v97, v96
	v_cmp_lt_f32_e64 s[4:5], 0, v97
	s_nop 1
	v_cndmask_b32_e64 v97, v98, v99, s[4:5]
	v_mul_f32_e32 v98, 0x37800000, v97
	v_cndmask_b32_e32 v97, v97, v98, vcc
	v_cmp_class_f32_e32 vcc, v96, v147
	s_nop 1
	v_cndmask_b32_e32 v96, v97, v96, vcc
	v_div_scale_f32 v97, s[4:5], v96, v96, 1.0
	v_rcp_f32_e32 v98, v97
	s_nop 0
	v_fma_f32 v99, -v97, v98, 1.0
	v_fmac_f32_e32 v98, v99, v98
	v_div_scale_f32 v99, vcc, 1.0, v96, 1.0
	v_mul_f32_e32 v100, v99, v98
	v_fma_f32 v101, -v97, v100, v99
	v_fmac_f32_e32 v100, v101, v98
	v_fma_f32 v97, -v97, v100, v99
	v_div_fmas_f32 v97, v97, v98, v100
	v_div_fixup_f32 v96, v97, v96, 1.0
; __device__ __forceinline__ unsigned pk2(float lo, float hi) { f32x2 v = {lo, hi}; bf16x2_t b = __builtin_convertvector(v, bf16x2_t); return __builtin_bit_cast(unsigned, b); }
; __device__ __forceinline__ void phase_rowpass(const Ctx& p, const float* F, int base_is_x, float alpha, const float* gpost, const float* gnext, bf16_t* XN, const float* PART, int nsplit) {
;     ...
;     for (int m = gw; m < MR; m += NGW) {
;         const bool more = m + NGW < MR;
;         if (more) loadrow(m + NGW, f2, b2);
;         float s = 0.f;
; #pragma unroll
;         for (int j = 0; j < 4; ++j) s += (f[j].x * f[j].x + f[j].y * f[j].y) + (f[j].z * f[j].z + f[j].w * f[j].w);
;         const float rs = alpha / sqrtf(wave_sum_fast(s) * (1.f / DM) + EPS);
;         float s2 = 0.f;
; #pragma unroll
;         for (int j = 0; j < 4; ++j) { b[j] = b[j] + f[j] * rs * gp[j]; s2 += (b[j].x * b[j].x + b[j].y * b[j].y) + (b[j].z * b[j].z + b[j].w * b[j].w);
;             ((f32x4*)(H + (size_t)m * DM))[lane + 64 * j] = b[j]; }
;         if (gnext) {
;             const float r2 = 1.f / sqrtf(wave_sum_fast(s2) * (1.f / DM) + EPS);
;             u32x2* o8 = (u32x2*)(XN + (size_t)m * DM) + lane;
; #pragma unroll
;             for (int j = 0; j < 4; ++j) { u32x2 w; w.x = pk2(b[j].x * r2 * gn[j].x, b[j].y * r2 * gn[j].y); w.y = pk2(b[j].z * r2 * gn[j].z, b[j].w * r2 * gn[j].w); o8[64 * j] = w; }
;         }
;         if (more) {
; #pragma unroll
;             for (int j = 0; j < 4; ++j) { f[j] = f2[j]; b[j] = b2[j]; } }
	v_mul_f32_e32 v0, v16, v96
	v_mul_f32_e32 v1, v17, v96
	v_mul_f32_e32 v2, v18, v96
	v_mul_f32_e32 v3, v19, v96
	v_mul_f32_e32 v4, v20, v96
	v_mul_f32_e32 v5, v21, v96
	v_mul_f32_e32 v6, v22, v96
	v_mul_f32_e32 v7, v23, v96
	v_mul_f32_e32 v8, v24, v96
	v_mul_f32_e32 v9, v25, v96
	v_mul_f32_e32 v10, v26, v96
	v_mul_f32_e32 v11, v27, v96
	v_mul_f32_e32 v12, v28, v96
	v_mul_f32_e32 v13, v29, v96
	v_mul_f32_e32 v14, v30, v96
	v_mul_f32_e32 v15, v31, v96
	v_mul_f32_e32 v0, v128, v0
	v_mul_f32_e32 v1, v129, v1
	v_mul_f32_e32 v2, v130, v2
	v_mul_f32_e32 v3, v131, v3
	v_mul_f32_e32 v4, v132, v4
	v_mul_f32_e32 v5, v133, v5
	v_mul_f32_e32 v6, v134, v6
	v_mul_f32_e32 v7, v135, v7
	v_mul_f32_e32 v8, v136, v8
	v_mul_f32_e32 v9, v137, v9
	v_mul_f32_e32 v10, v138, v10
	v_mul_f32_e32 v11, v139, v11
	v_mul_f32_e32 v12, v140, v12
	v_mul_f32_e32 v13, v141, v13
	v_mul_f32_e32 v14, v142, v14
	v_mul_f32_e32 v15, v143, v15
	v_cvt_pk_bf16_f32 v148, v0, v1
	v_cvt_pk_bf16_f32 v149, v2, v3
	global_store_dwordx2 v145, v[148:149], s[42:43] offset:0
	v_cvt_pk_bf16_f32 v150, v4, v5
	v_cvt_pk_bf16_f32 v151, v6, v7
	global_store_dwordx2 v145, v[150:151], s[42:43] offset:512
	v_cvt_pk_bf16_f32 v152, v8, v9
	v_cvt_pk_bf16_f32 v153, v10, v11
	global_store_dwordx2 v145, v[152:153], s[42:43] offset:1024
	v_cvt_pk_bf16_f32 v154, v12, v13
	v_cvt_pk_bf16_f32 v155, v14, v15
	global_store_dwordx2 v145, v[154:155], s[42:43] offset:1536
	s_add_u32 s40, s40, 0x1000
	s_addc_u32 s41, s41, 0
	s_add_u32 s42, s42, 0x800
	s_addc_u32 s43, s43, 0
	global_load_dwordx4 v[0:3], v144, s[24:25] offset:0
	global_load_dwordx4 v[4:7], v144, s[24:25] offset:1024
	global_load_dwordx4 v[8:11], v144, s[24:25] offset:2048
	global_load_dwordx4 v[12:15], v144, s[24:25] offset:3072
	global_load_dwordx4 v[16:19], v144, s[26:27] offset:0
	global_load_dwordx4 v[20:23], v144, s[26:27] offset:1024
	global_load_dwordx4 v[24:27], v144, s[26:27] offset:2048
	global_load_dwordx4 v[28:31], v144, s[26:27] offset:3072
	s_add_u32 s24, s24, 0x1000
	s_addc_u32 s25, s25, 0
	s_add_u32 s26, s26, 0x1000
	s_addc_u32 s27, s27, 0
	s_waitcnt vmcnt(32)
	v_mul_f32_e32 v96, v33, v33
	v_mul_f32_e32 v98, v35, v35
	v_fmac_f32_e32 v96, v32, v32
	v_fmac_f32_e32 v98, v34, v34
	v_add_f32_e32 v96, v96, v98
	v_mul_f32_e32 v97, v37, v37
	v_mul_f32_e32 v98, v39, v39
	v_fmac_f32_e32 v97, v36, v36
	v_fmac_f32_e32 v98, v38, v38
	v_add_f32_e32 v97, v97, v98
	v_add_f32_e32 v96, v97, v96
	v_mul_f32_e32 v97, v41, v41
	v_mul_f32_e32 v98, v43, v43
	v_fmac_f32_e32 v97, v40, v40
	v_fmac_f32_e32 v98, v42, v42
	v_add_f32_e32 v97, v97, v98
	v_add_f32_e32 v96, v97, v96
	v_mul_f32_e32 v97, v45, v45
	v_mul_f32_e32 v98, v47, v47
	v_fmac_f32_e32 v97, v44, v44
	v_fmac_f32_e32 v98, v46, v46
	v_add_f32_e32 v97, v97, v98
	v_add_f32_e32 v96, v97, v96
	s_nop 1
	v_add_f32_dpp v96, v96, v96 quad_perm:[1,0,3,2] row_mask:0xf bank_mask:0xf bound_ctrl:1
	s_nop 1
	v_add_f32_dpp v96, v96, v96 quad_perm:[2,3,0,1] row_mask:0xf bank_mask:0xf bound_ctrl:1
	s_nop 1
	v_add_f32_dpp v96, v96, v96 row_half_mirror row_mask:0xf bank_mask:0xf bound_ctrl:1
	s_nop 1
	v_add_f32_dpp v96, v96, v96 row_mirror row_mask:0xf bank_mask:0xf bound_ctrl:1
	v_mov_b32_e32 v97, v96
	s_nop 1
	v_permlane16_swap_b32_e32 v96, v97
	v_add_f32_e32 v96, v96, v97
	v_mov_b32_e32 v97, v96
	s_nop 1
	v_permlane32_swap_b32_e32 v96, v97
	v_add_f32_e32 v96, v96, v97
	v_fmamk_f32 v96, v96, 0x3a800000, v146
	v_mul_f32_e32 v97, 0x4f800000, v96
	v_cmp_gt_f32_e32 vcc, s33, v96
	s_nop 1
	v_cndmask_b32_e32 v96, v96, v97, vcc
	v_sqrt_f32_e32 v97, v96
	s_nop 0
	v_add_u32_e32 v98, -1, v97
	v_fma_f32 v99, -v98, v97, v96
	v_cmp_ge_f32_e64 s[4:5], 0, v99
	v_add_u32_e32 v99, 1, v97
	s_nop 0
	v_cndmask_b32_e64 v98, v97, v98, s[4:5]
	v_fma_f32 v97, -v99, v97, v96
	v_cmp_lt_f32_e64 s[4:5], 0, v97
	s_nop 1
	v_cndmask_b32_e64 v97, v98, v99, s[4:5]
	v_mul_f32_e32 v98, 0x37800000, v97
	v_cndmask_b32_e32 v97, v97, v98, vcc
	v_cmp_class_f32_e32 vcc, v96, v147
	s_nop 1
	v_cndmask_b32_e32 v96, v97, v96, vcc
	v_div_scale_f32 v97, s[4:5], v96, v96, 0.5
	v_rcp_f32_e32 v98, v97
	s_nop 0
	v_fma_f32 v99, -v97, v98, 1.0
	v_fmac_f32_e32 v98, v99, v98
	v_div_scale_f32 v99, vcc, 0.5, v96, 0.5
	v_mul_f32_e32 v100, v99, v98
	v_fma_f32 v101, -v97, v100, v99
	v_fmac_f32_e32 v100, v101, v98
	v_fma_f32 v97, -v97, v100, v99
	v_div_fmas_f32 v97, v97, v98, v100
	v_div_fixup_f32 v96, v97, v96, 0.5
	v_mul_f32_e32 v32, v32, v96
	v_mul_f32_e32 v33, v33, v96
	v_mul_f32_e32 v34, v34, v96
	v_mul_f32_e32 v35, v35, v96
	v_mul_f32_e32 v36, v36, v96
	v_mul_f32_e32 v37, v37, v96
	v_mul_f32_e32 v38, v38, v96
	v_mul_f32_e32 v39, v39, v96
	v_mul_f32_e32 v40, v40, v96
	v_mul_f32_e32 v41, v41, v96
	v_mul_f32_e32 v42, v42, v96
	v_mul_f32_e32 v43, v43, v96
	v_mul_f32_e32 v44, v44, v96
	v_mul_f32_e32 v45, v45, v96
	v_mul_f32_e32 v46, v46, v96
	v_mul_f32_e32 v47, v47, v96
	v_fmac_f32_e32 v48, v112, v32
	v_fmac_f32_e32 v49, v113, v33
	v_fmac_f32_e32 v50, v114, v34
	v_fmac_f32_e32 v51, v115, v35
	v_fmac_f32_e32 v52, v116, v36
	v_fmac_f32_e32 v53, v117, v37
	v_fmac_f32_e32 v54, v118, v38
	v_fmac_f32_e32 v55, v119, v39
	v_fmac_f32_e32 v56, v120, v40
	v_fmac_f32_e32 v57, v121, v41
	v_fmac_f32_e32 v58, v122, v42
	v_fmac_f32_e32 v59, v123, v43
	v_fmac_f32_e32 v60, v124, v44
	v_fmac_f32_e32 v61, v125, v45
	v_fmac_f32_e32 v62, v126, v46
	v_fmac_f32_e32 v63, v127, v47
	global_store_dwordx4 v144, v[48:51], s[40:41] offset:0
	global_store_dwordx4 v144, v[52:55], s[40:41] offset:1024
	global_store_dwordx4 v144, v[56:59], s[40:41] offset:2048
	global_store_dwordx4 v144, v[60:63], s[40:41] offset:3072
	v_mul_f32_e32 v96, v49, v49
	v_mul_f32_e32 v98, v51, v51
	v_fmac_f32_e32 v96, v48, v48
; __device__ __forceinline__ unsigned pk2(float lo, float hi) { f32x2 v = {lo, hi}; bf16x2_t b = __builtin_convertvector(v, bf16x2_t); return __builtin_bit_cast(unsigned, b); }
; __device__ __forceinline__ void phase_rowpass(const Ctx& p, const float* F, int base_is_x, float alpha, const float* gpost, const float* gnext, bf16_t* XN, const float* PART, int nsplit) {
;     ...
;         const float rs = alpha / sqrtf(wave_sum_fast(s) * (1.f / DM) + EPS);
;         float s2 = 0.f;
; #pragma unroll
;         for (int j = 0; j < 4; ++j) { b[j] = b[j] + f[j] * rs * gp[j]; s2 += (b[j].x * b[j].x + b[j].y * b[j].y) + (b[j].z * b[j].z + b[j].w * b[j].w);
;             ((f32x4*)(H + (size_t)m * DM))[lane + 64 * j] = b[j]; }
;         if (gnext) {
;             const float r2 = 1.f / sqrtf(wave_sum_fast(s2) * (1.f / DM) + EPS);
;             u32x2* o8 = (u32x2*)(XN + (size_t)m * DM) + lane;
; #pragma unroll
;             for (int j = 0; j < 4; ++j) { u32x2 w; w.x = pk2(b[j].x * r2 * gn[j].x, b[j].y * r2 * gn[j].y); w.y = pk2(b[j].z * r2 * gn[j].z, b[j].w * r2 * gn[j].w); o8[64 * j] = w; }
;         }
;         if (more) {
; #pragma unroll
;             for (int j = 0; j < 4; ++j) { f[j] = f2[j]; b[j] = b2[j]; } }
	v_fmac_f32_e32 v98, v50, v50
	v_add_f32_e32 v96, v96, v98
	v_mul_f32_e32 v97, v53, v53
	v_mul_f32_e32 v98, v55, v55
	v_fmac_f32_e32 v97, v52, v52
	v_fmac_f32_e32 v98, v54, v54
	v_add_f32_e32 v97, v97, v98
	v_add_f32_e32 v96, v97, v96
	v_mul_f32_e32 v97, v57, v57
	v_mul_f32_e32 v98, v59, v59
	v_fmac_f32_e32 v97, v56, v56
	v_fmac_f32_e32 v98, v58, v58
	v_add_f32_e32 v97, v97, v98
	v_add_f32_e32 v96, v97, v96
	v_mul_f32_e32 v97, v61, v61
	v_mul_f32_e32 v98, v63, v63
	v_fmac_f32_e32 v97, v60, v60
	v_fmac_f32_e32 v98, v62, v62
	v_add_f32_e32 v97, v97, v98
	v_add_f32_e32 v96, v97, v96
	s_nop 1
	v_add_f32_dpp v96, v96, v96 quad_perm:[1,0,3,2] row_mask:0xf bank_mask:0xf bound_ctrl:1
	s_nop 1
	v_add_f32_dpp v96, v96, v96 quad_perm:[2,3,0,1] row_mask:0xf bank_mask:0xf bound_ctrl:1
	s_nop 1
	v_add_f32_dpp v96, v96, v96 row_half_mirror row_mask:0xf bank_mask:0xf bound_ctrl:1
	s_nop 1
	v_add_f32_dpp v96, v96, v96 row_mirror row_mask:0xf bank_mask:0xf bound_ctrl:1
	v_mov_b32_e32 v97, v96
	s_nop 1
	v_permlane16_swap_b32_e32 v96, v97
	v_add_f32_e32 v96, v96, v97
	v_mov_b32_e32 v97, v96
	s_nop 1
	v_permlane32_swap_b32_e32 v96, v97
	v_add_f32_e32 v96, v96, v97
	v_fmamk_f32 v96, v96, 0x3a800000, v146
	v_mul_f32_e32 v97, 0x4f800000, v96
	v_cmp_gt_f32_e32 vcc, s33, v96
	s_nop 1
	v_cndmask_b32_e32 v96, v96, v97, vcc
	v_sqrt_f32_e32 v97, v96
	s_nop 0
	v_add_u32_e32 v98, -1, v97
	v_fma_f32 v99, -v98, v97, v96
	v_cmp_ge_f32_e64 s[4:5], 0, v99
	v_add_u32_e32 v99, 1, v97
	s_nop 0
	v_cndmask_b32_e64 v98, v97, v98, s[4:5]
	v_fma_f32 v97, -v99, v97, v96
	v_cmp_lt_f32_e64 s[4:5], 0, v97
	s_nop 1
	v_cndmask_b32_e64 v97, v98, v99, s[4:5]
	v_mul_f32_e32 v98, 0x37800000, v97
	v_cndmask_b32_e32 v97, v97, v98, vcc
	v_cmp_class_f32_e32 vcc, v96, v147
	s_nop 1
	v_cndmask_b32_e32 v96, v97, v96, vcc
	v_div_scale_f32 v97, s[4:5], v96, v96, 1.0
	v_rcp_f32_e32 v98, v97
	s_nop 0
	v_fma_f32 v99, -v97, v98, 1.0
	v_fmac_f32_e32 v98, v99, v98
	v_div_scale_f32 v99, vcc, 1.0, v96, 1.0
	v_mul_f32_e32 v100, v99, v98
	v_fma_f32 v101, -v97, v100, v99
	v_fmac_f32_e32 v100, v101, v98
	v_fma_f32 v97, -v97, v100, v99
	v_div_fmas_f32 v97, v97, v98, v100
	v_div_fixup_f32 v96, v97, v96, 1.0
	v_mul_f32_e32 v32, v48, v96
	v_mul_f32_e32 v33, v49, v96
	v_mul_f32_e32 v34, v50, v96
	v_mul_f32_e32 v35, v51, v96
	v_mul_f32_e32 v36, v52, v96
	v_mul_f32_e32 v37, v53, v96
	v_mul_f32_e32 v38, v54, v96
	v_mul_f32_e32 v39, v55, v96
	v_mul_f32_e32 v40, v56, v96
	v_mul_f32_e32 v41, v57, v96
	v_mul_f32_e32 v42, v58, v96
	v_mul_f32_e32 v43, v59, v96
	v_mul_f32_e32 v44, v60, v96
	v_mul_f32_e32 v45, v61, v96
	v_mul_f32_e32 v46, v62, v96
	v_mul_f32_e32 v47, v63, v96
	v_mul_f32_e32 v32, v128, v32
	v_mul_f32_e32 v33, v129, v33
	v_mul_f32_e32 v34, v130, v34
	v_mul_f32_e32 v35, v131, v35
	v_mul_f32_e32 v36, v132, v36
	v_mul_f32_e32 v37, v133, v37
	v_mul_f32_e32 v38, v134, v38
	v_mul_f32_e32 v39, v135, v39
	v_mul_f32_e32 v40, v136, v40
	v_mul_f32_e32 v41, v137, v41
	v_mul_f32_e32 v42, v138, v42
	v_mul_f32_e32 v43, v139, v43
	v_mul_f32_e32 v44, v140, v44
	v_mul_f32_e32 v45, v141, v45
	v_mul_f32_e32 v46, v142, v46
	v_mul_f32_e32 v47, v143, v47
	v_cvt_pk_bf16_f32 v148, v32, v33
	v_cvt_pk_bf16_f32 v149, v34, v35
	global_store_dwordx2 v145, v[148:149], s[42:43] offset:0
	v_cvt_pk_bf16_f32 v150, v36, v37
	v_cvt_pk_bf16_f32 v151, v38, v39
	global_store_dwordx2 v145, v[150:151], s[42:43] offset:512
	v_cvt_pk_bf16_f32 v152, v40, v41
	v_cvt_pk_bf16_f32 v153, v42, v43
	global_store_dwordx2 v145, v[152:153], s[42:43] offset:1024
	v_cvt_pk_bf16_f32 v154, v44, v45
	v_cvt_pk_bf16_f32 v155, v46, v47
	global_store_dwordx2 v145, v[154:155], s[42:43] offset:1536
	s_add_u32 s40, s40, 0x1000
	s_addc_u32 s41, s41, 0
	s_add_u32 s42, s42, 0x800
	s_addc_u32 s43, s43, 0
	global_load_dwordx4 v[32:35], v144, s[24:25] offset:0
	global_load_dwordx4 v[36:39], v144, s[24:25] offset:1024
	global_load_dwordx4 v[40:43], v144, s[24:25] offset:2048
	global_load_dwordx4 v[44:47], v144, s[24:25] offset:3072
	global_load_dwordx4 v[48:51], v144, s[26:27] offset:0
	global_load_dwordx4 v[52:55], v144, s[26:27] offset:1024
	global_load_dwordx4 v[56:59], v144, s[26:27] offset:2048
	global_load_dwordx4 v[60:63], v144, s[26:27] offset:3072
	s_add_u32 s24, s24, 0x1000
	s_addc_u32 s25, s25, 0
	s_add_u32 s26, s26, 0x1000
	s_addc_u32 s27, s27, 0
	s_waitcnt vmcnt(32)
; __device__ __forceinline__ unsigned pk2(float lo, float hi) { f32x2 v = {lo, hi}; bf16x2_t b = __builtin_convertvector(v, bf16x2_t); return __builtin_bit_cast(unsigned, b); }
; __device__ __forceinline__ void phase_rowpass(const Ctx& p, const float* F, int base_is_x, float alpha, const float* gpost, const float* gnext, bf16_t* XN, const float* PART, int nsplit) {
;     ...
;         float s = 0.f;
; #pragma unroll
;         for (int j = 0; j < 4; ++j) s += (f[j].x * f[j].x + f[j].y * f[j].y) + (f[j].z * f[j].z + f[j].w * f[j].w);
;         const float rs = alpha / sqrtf(wave_sum_fast(s) * (1.f / DM) + EPS);
;         float s2 = 0.f;
; #pragma unroll
;         for (int j = 0; j < 4; ++j) { b[j] = b[j] + f[j] * rs * gp[j]; s2 += (b[j].x * b[j].x + b[j].y * b[j].y) + (b[j].z * b[j].z + b[j].w * b[j].w);
;             ((f32x4*)(H + (size_t)m * DM))[lane + 64 * j] = b[j]; }
;         if (gnext) {
;             const float r2 = 1.f / sqrtf(wave_sum_fast(s2) * (1.f / DM) + EPS);
;             u32x2* o8 = (u32x2*)(XN + (size_t)m * DM) + lane;
; #pragma unroll
;             for (int j = 0; j < 4; ++j) { u32x2 w; w.x = pk2(b[j].x * r2 * gn[j].x, b[j].y * r2 * gn[j].y); w.y = pk2(b[j].z * r2 * gn[j].z, b[j].w * r2 * gn[j].w); o8[64 * j] = w; }
	v_mul_f32_e32 v96, v65, v65
	v_mul_f32_e32 v98, v67, v67
	v_fmac_f32_e32 v96, v64, v64
	v_fmac_f32_e32 v98, v66, v66
	v_add_f32_e32 v96, v96, v98
	v_mul_f32_e32 v97, v69, v69
	v_mul_f32_e32 v98, v71, v71
	v_fmac_f32_e32 v97, v68, v68
	v_fmac_f32_e32 v98, v70, v70
	v_add_f32_e32 v97, v97, v98
	v_add_f32_e32 v96, v97, v96
	v_mul_f32_e32 v97, v73, v73
	v_mul_f32_e32 v98, v75, v75
	v_fmac_f32_e32 v97, v72, v72
	v_fmac_f32_e32 v98, v74, v74
	v_add_f32_e32 v97, v97, v98
	v_add_f32_e32 v96, v97, v96
	v_mul_f32_e32 v97, v77, v77
	v_mul_f32_e32 v98, v79, v79
	v_fmac_f32_e32 v97, v76, v76
	v_fmac_f32_e32 v98, v78, v78
	v_add_f32_e32 v97, v97, v98
	v_add_f32_e32 v96, v97, v96
	s_nop 1
	v_add_f32_dpp v96, v96, v96 quad_perm:[1,0,3,2] row_mask:0xf bank_mask:0xf bound_ctrl:1
	s_nop 1
	v_add_f32_dpp v96, v96, v96 quad_perm:[2,3,0,1] row_mask:0xf bank_mask:0xf bound_ctrl:1
	s_nop 1
	v_add_f32_dpp v96, v96, v96 row_half_mirror row_mask:0xf bank_mask:0xf bound_ctrl:1
	s_nop 1
	v_add_f32_dpp v96, v96, v96 row_mirror row_mask:0xf bank_mask:0xf bound_ctrl:1
	v_mov_b32_e32 v97, v96
	s_nop 1
	v_permlane16_swap_b32_e32 v96, v97
	v_add_f32_e32 v96, v96, v97
	v_mov_b32_e32 v97, v96
	s_nop 1
	v_permlane32_swap_b32_e32 v96, v97
	v_add_f32_e32 v96, v96, v97
	v_fmamk_f32 v96, v96, 0x3a800000, v146
	v_mul_f32_e32 v97, 0x4f800000, v96
	v_cmp_gt_f32_e32 vcc, s33, v96
	s_nop 1
	v_cndmask_b32_e32 v96, v96, v97, vcc
	v_sqrt_f32_e32 v97, v96
	s_nop 0
	v_add_u32_e32 v98, -1, v97
	v_fma_f32 v99, -v98, v97, v96
	v_cmp_ge_f32_e64 s[4:5], 0, v99
	v_add_u32_e32 v99, 1, v97
	s_nop 0
	v_cndmask_b32_e64 v98, v97, v98, s[4:5]
	v_fma_f32 v97, -v99, v97, v96
	v_cmp_lt_f32_e64 s[4:5], 0, v97
	s_nop 1
	v_cndmask_b32_e64 v97, v98, v99, s[4:5]
	v_mul_f32_e32 v98, 0x37800000, v97
	v_cndmask_b32_e32 v97, v97, v98, vcc
	v_cmp_class_f32_e32 vcc, v96, v147
	s_nop 1
	v_cndmask_b32_e32 v96, v97, v96, vcc
	v_div_scale_f32 v97, s[4:5], v96, v96, 0.5
	v_rcp_f32_e32 v98, v97
	s_nop 0
	v_fma_f32 v99, -v97, v98, 1.0
	v_fmac_f32_e32 v98, v99, v98
	v_div_scale_f32 v99, vcc, 0.5, v96, 0.5
	v_mul_f32_e32 v100, v99, v98
	v_fma_f32 v101, -v97, v100, v99
	v_fmac_f32_e32 v100, v101, v98
	v_fma_f32 v97, -v97, v100, v99
	v_div_fmas_f32 v97, v97, v98, v100
	v_div_fixup_f32 v96, v97, v96, 0.5
	v_mul_f32_e32 v64, v64, v96
	v_mul_f32_e32 v65, v65, v96
	v_mul_f32_e32 v66, v66, v96
	v_mul_f32_e32 v67, v67, v96
	v_mul_f32_e32 v68, v68, v96
	v_mul_f32_e32 v69, v69, v96
	v_mul_f32_e32 v70, v70, v96
	v_mul_f32_e32 v71, v71, v96
	v_mul_f32_e32 v72, v72, v96
	v_mul_f32_e32 v73, v73, v96
	v_mul_f32_e32 v74, v74, v96
	v_mul_f32_e32 v75, v75, v96
	v_mul_f32_e32 v76, v76, v96
	v_mul_f32_e32 v77, v77, v96
	v_mul_f32_e32 v78, v78, v96
	v_mul_f32_e32 v79, v79, v96
	v_fmac_f32_e32 v80, v112, v64
	v_fmac_f32_e32 v81, v113, v65
	v_fmac_f32_e32 v82, v114, v66
	v_fmac_f32_e32 v83, v115, v67
	v_fmac_f32_e32 v84, v116, v68
	v_fmac_f32_e32 v85, v117, v69
	v_fmac_f32_e32 v86, v118, v70
	v_fmac_f32_e32 v87, v119, v71
	v_fmac_f32_e32 v88, v120, v72
	v_fmac_f32_e32 v89, v121, v73
	v_fmac_f32_e32 v90, v122, v74
	v_fmac_f32_e32 v91, v123, v75
	v_fmac_f32_e32 v92, v124, v76
	v_fmac_f32_e32 v93, v125, v77
	v_fmac_f32_e32 v94, v126, v78
	v_fmac_f32_e32 v95, v127, v79
	global_store_dwordx4 v144, v[80:83], s[40:41] offset:0
	global_store_dwordx4 v144, v[84:87], s[40:41] offset:1024
	global_store_dwordx4 v144, v[88:91], s[40:41] offset:2048
	global_store_dwordx4 v144, v[92:95], s[40:41] offset:3072
	v_mul_f32_e32 v96, v81, v81
	v_mul_f32_e32 v98, v83, v83
	v_fmac_f32_e32 v96, v80, v80
	v_fmac_f32_e32 v98, v82, v82
	v_add_f32_e32 v96, v96, v98
	v_mul_f32_e32 v97, v85, v85
	v_mul_f32_e32 v98, v87, v87
	v_fmac_f32_e32 v97, v84, v84
	v_fmac_f32_e32 v98, v86, v86
	v_add_f32_e32 v97, v97, v98
	v_add_f32_e32 v96, v97, v96
	v_mul_f32_e32 v97, v89, v89
	v_mul_f32_e32 v98, v91, v91
	v_fmac_f32_e32 v97, v88, v88
	v_fmac_f32_e32 v98, v90, v90
	v_add_f32_e32 v97, v97, v98
	v_add_f32_e32 v96, v97, v96
	v_mul_f32_e32 v97, v93, v93
	v_mul_f32_e32 v98, v95, v95
	v_fmac_f32_e32 v97, v92, v92
	v_fmac_f32_e32 v98, v94, v94
	v_add_f32_e32 v97, v97, v98
	v_add_f32_e32 v96, v97, v96
	s_nop 1
	v_add_f32_dpp v96, v96, v96 quad_perm:[1,0,3,2] row_mask:0xf bank_mask:0xf bound_ctrl:1
	s_nop 1
	v_add_f32_dpp v96, v96, v96 quad_perm:[2,3,0,1] row_mask:0xf bank_mask:0xf bound_ctrl:1
	s_nop 1
	v_add_f32_dpp v96, v96, v96 row_half_mirror row_mask:0xf bank_mask:0xf bound_ctrl:1
	s_nop 1
	v_add_f32_dpp v96, v96, v96 row_mirror row_mask:0xf bank_mask:0xf bound_ctrl:1
	v_mov_b32_e32 v97, v96
	s_nop 1
	v_permlane16_swap_b32_e32 v96, v97
	v_add_f32_e32 v96, v96, v97
	v_mov_b32_e32 v97, v96
	s_nop 1
	v_permlane32_swap_b32_e32 v96, v97
	v_add_f32_e32 v96, v96, v97
	v_fmamk_f32 v96, v96, 0x3a800000, v146
	v_mul_f32_e32 v97, 0x4f800000, v96
	v_cmp_gt_f32_e32 vcc, s33, v96
	s_nop 1
	v_cndmask_b32_e32 v96, v96, v97, vcc
	v_sqrt_f32_e32 v97, v96
	s_nop 0
	v_add_u32_e32 v98, -1, v97
	v_fma_f32 v99, -v98, v97, v96
	v_cmp_ge_f32_e64 s[4:5], 0, v99
	v_add_u32_e32 v99, 1, v97
	s_nop 0
	v_cndmask_b32_e64 v98, v97, v98, s[4:5]
	v_fma_f32 v97, -v99, v97, v96
	v_cmp_lt_f32_e64 s[4:5], 0, v97
	s_nop 1
	v_cndmask_b32_e64 v97, v98, v99, s[4:5]
	v_mul_f32_e32 v98, 0x37800000, v97
	v_cndmask_b32_e32 v97, v97, v98, vcc
	v_cmp_class_f32_e32 vcc, v96, v147
	s_nop 1
	v_cndmask_b32_e32 v96, v97, v96, vcc
	v_div_scale_f32 v97, s[4:5], v96, v96, 1.0
	v_rcp_f32_e32 v98, v97
	s_nop 0
	v_fma_f32 v99, -v97, v98, 1.0
	v_fmac_f32_e32 v98, v99, v98
	v_div_scale_f32 v99, vcc, 1.0, v96, 1.0
	v_mul_f32_e32 v100, v99, v98
	v_fma_f32 v101, -v97, v100, v99
	v_fmac_f32_e32 v100, v101, v98
	v_fma_f32 v97, -v97, v100, v99
; __device__ __forceinline__ unsigned pk2(float lo, float hi) { f32x2 v = {lo, hi}; bf16x2_t b = __builtin_convertvector(v, bf16x2_t); return __builtin_bit_cast(unsigned, b); }
; __device__ __forceinline__ void phase_rowpass(const Ctx& p, const float* F, int base_is_x, float alpha, const float* gpost, const float* gnext, bf16_t* XN, const float* PART, int nsplit) {
;     ...
;         float s = 0.f;
; #pragma unroll
;         for (int j = 0; j < 4; ++j) s += (f[j].x * f[j].x + f[j].y * f[j].y) + (f[j].z * f[j].z + f[j].w * f[j].w);
;         const float rs = alpha / sqrtf(wave_sum_fast(s) * (1.f / DM) + EPS);
;         float s2 = 0.f;
; #pragma unroll
;         for (int j = 0; j < 4; ++j) { b[j] = b[j] + f[j] * rs * gp[j]; s2 += (b[j].x * b[j].x + b[j].y * b[j].y) + (b[j].z * b[j].z + b[j].w * b[j].w);
;             ((f32x4*)(H + (size_t)m * DM))[lane + 64 * j] = b[j]; }
;     ...
;             const float r2 = 1.f / sqrtf(wave_sum_fast(s2) * (1.f / DM) + EPS);
;             u32x2* o8 = (u32x2*)(XN + (size_t)m * DM) + lane;
; #pragma unroll
;             for (int j = 0; j < 4; ++j) { u32x2 w; w.x = pk2(b[j].x * r2 * gn[j].x, b[j].y * r2 * gn[j].y); w.y = pk2(b[j].z * r2 * gn[j].z, b[j].w * r2 * gn[j].w); o8[64 * j] = w; }
	v_div_fmas_f32 v97, v97, v98, v100
	v_div_fixup_f32 v96, v97, v96, 1.0
	v_mul_f32_e32 v64, v80, v96
	v_mul_f32_e32 v65, v81, v96
	v_mul_f32_e32 v66, v82, v96
	v_mul_f32_e32 v67, v83, v96
	v_mul_f32_e32 v68, v84, v96
	v_mul_f32_e32 v69, v85, v96
	v_mul_f32_e32 v70, v86, v96
	v_mul_f32_e32 v71, v87, v96
	v_mul_f32_e32 v72, v88, v96
	v_mul_f32_e32 v73, v89, v96
	v_mul_f32_e32 v74, v90, v96
	v_mul_f32_e32 v75, v91, v96
	v_mul_f32_e32 v76, v92, v96
	v_mul_f32_e32 v77, v93, v96
	v_mul_f32_e32 v78, v94, v96
	v_mul_f32_e32 v79, v95, v96
	v_mul_f32_e32 v64, v128, v64
	v_mul_f32_e32 v65, v129, v65
	v_mul_f32_e32 v66, v130, v66
	v_mul_f32_e32 v67, v131, v67
	v_mul_f32_e32 v68, v132, v68
	v_mul_f32_e32 v69, v133, v69
	v_mul_f32_e32 v70, v134, v70
	v_mul_f32_e32 v71, v135, v71
	v_mul_f32_e32 v72, v136, v72
	v_mul_f32_e32 v73, v137, v73
	v_mul_f32_e32 v74, v138, v74
	v_mul_f32_e32 v75, v139, v75
	v_mul_f32_e32 v76, v140, v76
	v_mul_f32_e32 v77, v141, v77
	v_mul_f32_e32 v78, v142, v78
	v_mul_f32_e32 v79, v143, v79
	v_cvt_pk_bf16_f32 v148, v64, v65
	v_cvt_pk_bf16_f32 v149, v66, v67
	global_store_dwordx2 v145, v[148:149], s[42:43] offset:0
	v_cvt_pk_bf16_f32 v150, v68, v69
	v_cvt_pk_bf16_f32 v151, v70, v71
	global_store_dwordx2 v145, v[150:151], s[42:43] offset:512
	v_cvt_pk_bf16_f32 v152, v72, v73
	v_cvt_pk_bf16_f32 v153, v74, v75
	global_store_dwordx2 v145, v[152:153], s[42:43] offset:1024
	v_cvt_pk_bf16_f32 v154, v76, v77
	v_cvt_pk_bf16_f32 v155, v78, v79
	global_store_dwordx2 v145, v[154:155], s[42:43] offset:1536
	s_add_u32 s40, s40, 0x1000
	s_addc_u32 s41, s41, 0
	s_add_u32 s42, s42, 0x800
	s_addc_u32 s43, s43, 0
	s_waitcnt vmcnt(24)
	v_mul_f32_e32 v96, v1, v1
	v_mul_f32_e32 v98, v3, v3
	v_fmac_f32_e32 v96, v0, v0
	v_fmac_f32_e32 v98, v2, v2
	v_add_f32_e32 v96, v96, v98
	v_mul_f32_e32 v97, v5, v5
	v_mul_f32_e32 v98, v7, v7
	v_fmac_f32_e32 v97, v4, v4
	v_fmac_f32_e32 v98, v6, v6
	v_add_f32_e32 v97, v97, v98
	v_add_f32_e32 v96, v97, v96
	v_mul_f32_e32 v97, v9, v9
	v_mul_f32_e32 v98, v11, v11
	v_fmac_f32_e32 v97, v8, v8
	v_fmac_f32_e32 v98, v10, v10
	v_add_f32_e32 v97, v97, v98
	v_add_f32_e32 v96, v97, v96
	v_mul_f32_e32 v97, v13, v13
	v_mul_f32_e32 v98, v15, v15
	v_fmac_f32_e32 v97, v12, v12
	v_fmac_f32_e32 v98, v14, v14
	v_add_f32_e32 v97, v97, v98
	v_add_f32_e32 v96, v97, v96
	s_nop 1
	v_add_f32_dpp v96, v96, v96 quad_perm:[1,0,3,2] row_mask:0xf bank_mask:0xf bound_ctrl:1
	s_nop 1
	v_add_f32_dpp v96, v96, v96 quad_perm:[2,3,0,1] row_mask:0xf bank_mask:0xf bound_ctrl:1
	s_nop 1
	v_add_f32_dpp v96, v96, v96 row_half_mirror row_mask:0xf bank_mask:0xf bound_ctrl:1
	s_nop 1
	v_add_f32_dpp v96, v96, v96 row_mirror row_mask:0xf bank_mask:0xf bound_ctrl:1
	v_mov_b32_e32 v97, v96
	s_nop 1
	v_permlane16_swap_b32_e32 v96, v97
	v_add_f32_e32 v96, v96, v97
	v_mov_b32_e32 v97, v96
	s_nop 1
	v_permlane32_swap_b32_e32 v96, v97
	v_add_f32_e32 v96, v96, v97
	v_fmamk_f32 v96, v96, 0x3a800000, v146
	v_mul_f32_e32 v97, 0x4f800000, v96
	v_cmp_gt_f32_e32 vcc, s33, v96
	s_nop 1
	v_cndmask_b32_e32 v96, v96, v97, vcc
	v_sqrt_f32_e32 v97, v96
	s_nop 0
	v_add_u32_e32 v98, -1, v97
	v_fma_f32 v99, -v98, v97, v96
	v_cmp_ge_f32_e64 s[4:5], 0, v99
	v_add_u32_e32 v99, 1, v97
	s_nop 0
	v_cndmask_b32_e64 v98, v97, v98, s[4:5]
	v_fma_f32 v97, -v99, v97, v96
	v_cmp_lt_f32_e64 s[4:5], 0, v97
	s_nop 1
	v_cndmask_b32_e64 v97, v98, v99, s[4:5]
	v_mul_f32_e32 v98, 0x37800000, v97
	v_cndmask_b32_e32 v97, v97, v98, vcc
	v_cmp_class_f32_e32 vcc, v96, v147
	s_nop 1
	v_cndmask_b32_e32 v96, v97, v96, vcc
	v_div_scale_f32 v97, s[4:5], v96, v96, 0.5
	v_rcp_f32_e32 v98, v97
	s_nop 0
	v_fma_f32 v99, -v97, v98, 1.0
	v_fmac_f32_e32 v98, v99, v98
	v_div_scale_f32 v99, vcc, 0.5, v96, 0.5
	v_mul_f32_e32 v100, v99, v98
	v_fma_f32 v101, -v97, v100, v99
	v_fmac_f32_e32 v100, v101, v98
	v_fma_f32 v97, -v97, v100, v99
	v_div_fmas_f32 v97, v97, v98, v100
	v_div_fixup_f32 v96, v97, v96, 0.5
	v_mul_f32_e32 v0, v0, v96
	v_mul_f32_e32 v1, v1, v96
	v_mul_f32_e32 v2, v2, v96
	v_mul_f32_e32 v3, v3, v96
	v_mul_f32_e32 v4, v4, v96
	v_mul_f32_e32 v5, v5, v96
	v_mul_f32_e32 v6, v6, v96
	v_mul_f32_e32 v7, v7, v96
	v_mul_f32_e32 v8, v8, v96
	v_mul_f32_e32 v9, v9, v96
	v_mul_f32_e32 v10, v10, v96
	v_mul_f32_e32 v11, v11, v96
	v_mul_f32_e32 v12, v12, v96
	v_mul_f32_e32 v13, v13, v96
	v_mul_f32_e32 v14, v14, v96
	v_mul_f32_e32 v15, v15, v96
	v_fmac_f32_e32 v16, v112, v0
	v_fmac_f32_e32 v17, v113, v1
	v_fmac_f32_e32 v18, v114, v2
	v_fmac_f32_e32 v19, v115, v3
	v_fmac_f32_e32 v20, v116, v4
	v_fmac_f32_e32 v21, v117, v5
	v_fmac_f32_e32 v22, v118, v6
	v_fmac_f32_e32 v23, v119, v7
	v_fmac_f32_e32 v24, v120, v8
	v_fmac_f32_e32 v25, v121, v9
	v_fmac_f32_e32 v26, v122, v10
	v_fmac_f32_e32 v27, v123, v11
	v_fmac_f32_e32 v28, v124, v12
	v_fmac_f32_e32 v29, v125, v13
	v_fmac_f32_e32 v30, v126, v14
	v_fmac_f32_e32 v31, v127, v15
	global_store_dwordx4 v144, v[16:19], s[40:41] offset:0
	global_store_dwordx4 v144, v[20:23], s[40:41] offset:1024
	global_store_dwordx4 v144, v[24:27], s[40:41] offset:2048
	global_store_dwordx4 v144, v[28:31], s[40:41] offset:3072
	v_mul_f32_e32 v96, v17, v17
	v_mul_f32_e32 v98, v19, v19
	v_fmac_f32_e32 v96, v16, v16
	v_fmac_f32_e32 v98, v18, v18
	v_add_f32_e32 v96, v96, v98
	v_mul_f32_e32 v97, v21, v21
	v_mul_f32_e32 v98, v23, v23
	v_fmac_f32_e32 v97, v20, v20
	v_fmac_f32_e32 v98, v22, v22
	v_add_f32_e32 v97, v97, v98
	v_add_f32_e32 v96, v97, v96
	v_mul_f32_e32 v97, v25, v25
	v_mul_f32_e32 v98, v27, v27
	v_fmac_f32_e32 v97, v24, v24
	v_fmac_f32_e32 v98, v26, v26
	v_add_f32_e32 v97, v97, v98
	v_add_f32_e32 v96, v97, v96
	v_mul_f32_e32 v97, v29, v29
	v_mul_f32_e32 v98, v31, v31
	v_fmac_f32_e32 v97, v28, v28
; __device__ __forceinline__ unsigned pk2(float lo, float hi) { f32x2 v = {lo, hi}; bf16x2_t b = __builtin_convertvector(v, bf16x2_t); return __builtin_bit_cast(unsigned, b); }
; __device__ __forceinline__ void phase_rowpass(const Ctx& p, const float* F, int base_is_x, float alpha, const float* gpost, const float* gnext, bf16_t* XN, const float* PART, int nsplit) {
;     ...
;         float s = 0.f;
; #pragma unroll
;         for (int j = 0; j < 4; ++j) s += (f[j].x * f[j].x + f[j].y * f[j].y) + (f[j].z * f[j].z + f[j].w * f[j].w);
;         const float rs = alpha / sqrtf(wave_sum_fast(s) * (1.f / DM) + EPS);
;     ...
;             const float r2 = 1.f / sqrtf(wave_sum_fast(s2) * (1.f / DM) + EPS);
;             u32x2* o8 = (u32x2*)(XN + (size_t)m * DM) + lane;
; #pragma unroll
;             for (int j = 0; j < 4; ++j) { u32x2 w; w.x = pk2(b[j].x * r2 * gn[j].x, b[j].y * r2 * gn[j].y); w.y = pk2(b[j].z * r2 * gn[j].z, b[j].w * r2 * gn[j].w); o8[64 * j] = w; }
	v_fmac_f32_e32 v98, v30, v30
	v_add_f32_e32 v97, v97, v98
	v_add_f32_e32 v96, v97, v96
	s_nop 1
	v_add_f32_dpp v96, v96, v96 quad_perm:[1,0,3,2] row_mask:0xf bank_mask:0xf bound_ctrl:1
	s_nop 1
	v_add_f32_dpp v96, v96, v96 quad_perm:[2,3,0,1] row_mask:0xf bank_mask:0xf bound_ctrl:1
	s_nop 1
	v_add_f32_dpp v96, v96, v96 row_half_mirror row_mask:0xf bank_mask:0xf bound_ctrl:1
	s_nop 1
	v_add_f32_dpp v96, v96, v96 row_mirror row_mask:0xf bank_mask:0xf bound_ctrl:1
	v_mov_b32_e32 v97, v96
	s_nop 1
	v_permlane16_swap_b32_e32 v96, v97
	v_add_f32_e32 v96, v96, v97
	v_mov_b32_e32 v97, v96
	s_nop 1
	v_permlane32_swap_b32_e32 v96, v97
	v_add_f32_e32 v96, v96, v97
	v_fmamk_f32 v96, v96, 0x3a800000, v146
	v_mul_f32_e32 v97, 0x4f800000, v96
	v_cmp_gt_f32_e32 vcc, s33, v96
	s_nop 1
	v_cndmask_b32_e32 v96, v96, v97, vcc
	v_sqrt_f32_e32 v97, v96
	s_nop 0
	v_add_u32_e32 v98, -1, v97
	v_fma_f32 v99, -v98, v97, v96
	v_cmp_ge_f32_e64 s[4:5], 0, v99
	v_add_u32_e32 v99, 1, v97
	s_nop 0
	v_cndmask_b32_e64 v98, v97, v98, s[4:5]
	v_fma_f32 v97, -v99, v97, v96
	v_cmp_lt_f32_e64 s[4:5], 0, v97
	s_nop 1
	v_cndmask_b32_e64 v97, v98, v99, s[4:5]
	v_mul_f32_e32 v98, 0x37800000, v97
	v_cndmask_b32_e32 v97, v97, v98, vcc
	v_cmp_class_f32_e32 vcc, v96, v147
	s_nop 1
	v_cndmask_b32_e32 v96, v97, v96, vcc
	v_div_scale_f32 v97, s[4:5], v96, v96, 1.0
	v_rcp_f32_e32 v98, v97
	s_nop 0
	v_fma_f32 v99, -v97, v98, 1.0
	v_fmac_f32_e32 v98, v99, v98
	v_div_scale_f32 v99, vcc, 1.0, v96, 1.0
	v_mul_f32_e32 v100, v99, v98
	v_fma_f32 v101, -v97, v100, v99
	v_fmac_f32_e32 v100, v101, v98
	v_fma_f32 v97, -v97, v100, v99
	v_div_fmas_f32 v97, v97, v98, v100
	v_div_fixup_f32 v96, v97, v96, 1.0
	v_mul_f32_e32 v0, v16, v96
	v_mul_f32_e32 v1, v17, v96
	v_mul_f32_e32 v2, v18, v96
	v_mul_f32_e32 v3, v19, v96
	v_mul_f32_e32 v4, v20, v96
	v_mul_f32_e32 v5, v21, v96
	v_mul_f32_e32 v6, v22, v96
	v_mul_f32_e32 v7, v23, v96
	v_mul_f32_e32 v8, v24, v96
	v_mul_f32_e32 v9, v25, v96
	v_mul_f32_e32 v10, v26, v96
	v_mul_f32_e32 v11, v27, v96
	v_mul_f32_e32 v12, v28, v96
	v_mul_f32_e32 v13, v29, v96
	v_mul_f32_e32 v14, v30, v96
	v_mul_f32_e32 v15, v31, v96
	v_mul_f32_e32 v0, v128, v0
	v_mul_f32_e32 v1, v129, v1
	v_mul_f32_e32 v2, v130, v2
	v_mul_f32_e32 v3, v131, v3
	v_mul_f32_e32 v4, v132, v4
	v_mul_f32_e32 v5, v133, v5
	v_mul_f32_e32 v6, v134, v6
	v_mul_f32_e32 v7, v135, v7
	v_mul_f32_e32 v8, v136, v8
	v_mul_f32_e32 v9, v137, v9
	v_mul_f32_e32 v10, v138, v10
	v_mul_f32_e32 v11, v139, v11
	v_mul_f32_e32 v12, v140, v12
	v_mul_f32_e32 v13, v141, v13
	v_mul_f32_e32 v14, v142, v14
	v_mul_f32_e32 v15, v143, v15
	v_cvt_pk_bf16_f32 v148, v0, v1
	v_cvt_pk_bf16_f32 v149, v2, v3
	global_store_dwordx2 v145, v[148:149], s[42:43] offset:0
	v_cvt_pk_bf16_f32 v150, v4, v5
	v_cvt_pk_bf16_f32 v151, v6, v7
	global_store_dwordx2 v145, v[150:151], s[42:43] offset:512
	v_cvt_pk_bf16_f32 v152, v8, v9
	v_cvt_pk_bf16_f32 v153, v10, v11
	global_store_dwordx2 v145, v[152:153], s[42:43] offset:1024
	v_cvt_pk_bf16_f32 v154, v12, v13
	v_cvt_pk_bf16_f32 v155, v14, v15
	global_store_dwordx2 v145, v[154:155], s[42:43] offset:1536
	s_add_u32 s40, s40, 0x1000
	s_addc_u32 s41, s41, 0
	s_add_u32 s42, s42, 0x800
	s_addc_u32 s43, s43, 0
	s_waitcnt vmcnt(16)
	v_mul_f32_e32 v96, v33, v33
	v_mul_f32_e32 v98, v35, v35
	v_fmac_f32_e32 v96, v32, v32
	v_fmac_f32_e32 v98, v34, v34
	v_add_f32_e32 v96, v96, v98
	v_mul_f32_e32 v97, v37, v37
	v_mul_f32_e32 v98, v39, v39
	v_fmac_f32_e32 v97, v36, v36
	v_fmac_f32_e32 v98, v38, v38
	v_add_f32_e32 v97, v97, v98
	v_add_f32_e32 v96, v97, v96
	v_mul_f32_e32 v97, v41, v41
	v_mul_f32_e32 v98, v43, v43
	v_fmac_f32_e32 v97, v40, v40
	v_fmac_f32_e32 v98, v42, v42
	v_add_f32_e32 v97, v97, v98
	v_add_f32_e32 v96, v97, v96
	v_mul_f32_e32 v97, v45, v45
	v_mul_f32_e32 v98, v47, v47
	v_fmac_f32_e32 v97, v44, v44
	v_fmac_f32_e32 v98, v46, v46
	v_add_f32_e32 v97, v97, v98
	v_add_f32_e32 v96, v97, v96
	s_nop 1
	v_add_f32_dpp v96, v96, v96 quad_perm:[1,0,3,2] row_mask:0xf bank_mask:0xf bound_ctrl:1
	s_nop 1
	v_add_f32_dpp v96, v96, v96 quad_perm:[2,3,0,1] row_mask:0xf bank_mask:0xf bound_ctrl:1
	s_nop 1
	v_add_f32_dpp v96, v96, v96 row_half_mirror row_mask:0xf bank_mask:0xf bound_ctrl:1
	s_nop 1
	v_add_f32_dpp v96, v96, v96 row_mirror row_mask:0xf bank_mask:0xf bound_ctrl:1
	v_mov_b32_e32 v97, v96
	s_nop 1
	v_permlane16_swap_b32_e32 v96, v97
	v_add_f32_e32 v96, v96, v97
	v_mov_b32_e32 v97, v96
	s_nop 1
	v_permlane32_swap_b32_e32 v96, v97
	v_add_f32_e32 v96, v96, v97
	v_fmamk_f32 v96, v96, 0x3a800000, v146
	v_mul_f32_e32 v97, 0x4f800000, v96
	v_cmp_gt_f32_e32 vcc, s33, v96
	s_nop 1
	v_cndmask_b32_e32 v96, v96, v97, vcc
	v_sqrt_f32_e32 v97, v96
	s_nop 0
	v_add_u32_e32 v98, -1, v97
	v_fma_f32 v99, -v98, v97, v96
	v_cmp_ge_f32_e64 s[4:5], 0, v99
	v_add_u32_e32 v99, 1, v97
	s_nop 0
	v_cndmask_b32_e64 v98, v97, v98, s[4:5]
	v_fma_f32 v97, -v99, v97, v96
	v_cmp_lt_f32_e64 s[4:5], 0, v97
	s_nop 1
	v_cndmask_b32_e64 v97, v98, v99, s[4:5]
	v_mul_f32_e32 v98, 0x37800000, v97
	v_cndmask_b32_e32 v97, v97, v98, vcc
	v_cmp_class_f32_e32 vcc, v96, v147
	s_nop 1
	v_cndmask_b32_e32 v96, v97, v96, vcc
	v_div_scale_f32 v97, s[4:5], v96, v96, 0.5
	v_rcp_f32_e32 v98, v97
	s_nop 0
	v_fma_f32 v99, -v97, v98, 1.0
	v_fmac_f32_e32 v98, v99, v98
	v_div_scale_f32 v99, vcc, 0.5, v96, 0.5
	v_mul_f32_e32 v100, v99, v98
	v_fma_f32 v101, -v97, v100, v99
	v_fmac_f32_e32 v100, v101, v98
	v_fma_f32 v97, -v97, v100, v99
	v_div_fmas_f32 v97, v97, v98, v100
	v_div_fixup_f32 v96, v97, v96, 0.5
; __device__ __forceinline__ unsigned pk2(float lo, float hi) { f32x2 v = {lo, hi}; bf16x2_t b = __builtin_convertvector(v, bf16x2_t); return __builtin_bit_cast(unsigned, b); }
; __device__ __forceinline__ void phase_rowpass(const Ctx& p, const float* F, int base_is_x, float alpha, const float* gpost, const float* gnext, bf16_t* XN, const float* PART, int nsplit) {
;     ...
;         for (int j = 0; j < 4; ++j) { b[j] = b[j] + f[j] * rs * gp[j]; s2 += (b[j].x * b[j].x + b[j].y * b[j].y) + (b[j].z * b[j].z + b[j].w * b[j].w);
;             ((f32x4*)(H + (size_t)m * DM))[lane + 64 * j] = b[j]; }
;         if (gnext) {
;             const float r2 = 1.f / sqrtf(wave_sum_fast(s2) * (1.f / DM) + EPS);
;             u32x2* o8 = (u32x2*)(XN + (size_t)m * DM) + lane;
; #pragma unroll
;             for (int j = 0; j < 4; ++j) { u32x2 w; w.x = pk2(b[j].x * r2 * gn[j].x, b[j].y * r2 * gn[j].y); w.y = pk2(b[j].z * r2 * gn[j].z, b[j].w * r2 * gn[j].w); o8[64 * j] = w; }
	v_mul_f32_e32 v32, v32, v96
	v_mul_f32_e32 v33, v33, v96
	v_mul_f32_e32 v34, v34, v96
	v_mul_f32_e32 v35, v35, v96
	v_mul_f32_e32 v36, v36, v96
	v_mul_f32_e32 v37, v37, v96
	v_mul_f32_e32 v38, v38, v96
	v_mul_f32_e32 v39, v39, v96
	v_mul_f32_e32 v40, v40, v96
	v_mul_f32_e32 v41, v41, v96
	v_mul_f32_e32 v42, v42, v96
	v_mul_f32_e32 v43, v43, v96
	v_mul_f32_e32 v44, v44, v96
	v_mul_f32_e32 v45, v45, v96
	v_mul_f32_e32 v46, v46, v96
	v_mul_f32_e32 v47, v47, v96
	v_fmac_f32_e32 v48, v112, v32
	v_fmac_f32_e32 v49, v113, v33
	v_fmac_f32_e32 v50, v114, v34
	v_fmac_f32_e32 v51, v115, v35
	v_fmac_f32_e32 v52, v116, v36
	v_fmac_f32_e32 v53, v117, v37
	v_fmac_f32_e32 v54, v118, v38
	v_fmac_f32_e32 v55, v119, v39
	v_fmac_f32_e32 v56, v120, v40
	v_fmac_f32_e32 v57, v121, v41
	v_fmac_f32_e32 v58, v122, v42
	v_fmac_f32_e32 v59, v123, v43
	v_fmac_f32_e32 v60, v124, v44
	v_fmac_f32_e32 v61, v125, v45
	v_fmac_f32_e32 v62, v126, v46
	v_fmac_f32_e32 v63, v127, v47
	global_store_dwordx4 v144, v[48:51], s[40:41] offset:0
	global_store_dwordx4 v144, v[52:55], s[40:41] offset:1024
	global_store_dwordx4 v144, v[56:59], s[40:41] offset:2048
	global_store_dwordx4 v144, v[60:63], s[40:41] offset:3072
	v_mul_f32_e32 v96, v49, v49
	v_mul_f32_e32 v98, v51, v51
	v_fmac_f32_e32 v96, v48, v48
	v_fmac_f32_e32 v98, v50, v50
	v_add_f32_e32 v96, v96, v98
	v_mul_f32_e32 v97, v53, v53
	v_mul_f32_e32 v98, v55, v55
	v_fmac_f32_e32 v97, v52, v52
	v_fmac_f32_e32 v98, v54, v54
	v_add_f32_e32 v97, v97, v98
	v_add_f32_e32 v96, v97, v96
	v_mul_f32_e32 v97, v57, v57
	v_mul_f32_e32 v98, v59, v59
	v_fmac_f32_e32 v97, v56, v56
	v_fmac_f32_e32 v98, v58, v58
	v_add_f32_e32 v97, v97, v98
	v_add_f32_e32 v96, v97, v96
	v_mul_f32_e32 v97, v61, v61
	v_mul_f32_e32 v98, v63, v63
	v_fmac_f32_e32 v97, v60, v60
	v_fmac_f32_e32 v98, v62, v62
	v_add_f32_e32 v97, v97, v98
	v_add_f32_e32 v96, v97, v96
	s_nop 1
	v_add_f32_dpp v96, v96, v96 quad_perm:[1,0,3,2] row_mask:0xf bank_mask:0xf bound_ctrl:1
	s_nop 1
	v_add_f32_dpp v96, v96, v96 quad_perm:[2,3,0,1] row_mask:0xf bank_mask:0xf bound_ctrl:1
	s_nop 1
	v_add_f32_dpp v96, v96, v96 row_half_mirror row_mask:0xf bank_mask:0xf bound_ctrl:1
	s_nop 1
	v_add_f32_dpp v96, v96, v96 row_mirror row_mask:0xf bank_mask:0xf bound_ctrl:1
	v_mov_b32_e32 v97, v96
	s_nop 1
	v_permlane16_swap_b32_e32 v96, v97
	v_add_f32_e32 v96, v96, v97
	v_mov_b32_e32 v97, v96
	s_nop 1
	v_permlane32_swap_b32_e32 v96, v97
	v_add_f32_e32 v96, v96, v97
	v_fmamk_f32 v96, v96, 0x3a800000, v146
	v_mul_f32_e32 v97, 0x4f800000, v96
	v_cmp_gt_f32_e32 vcc, s33, v96
	s_nop 1
	v_cndmask_b32_e32 v96, v96, v97, vcc
	v_sqrt_f32_e32 v97, v96
	s_nop 0
	v_add_u32_e32 v98, -1, v97
	v_fma_f32 v99, -v98, v97, v96
	v_cmp_ge_f32_e64 s[4:5], 0, v99
	v_add_u32_e32 v99, 1, v97
	s_nop 0
	v_cndmask_b32_e64 v98, v97, v98, s[4:5]
	v_fma_f32 v97, -v99, v97, v96
	v_cmp_lt_f32_e64 s[4:5], 0, v97
	s_nop 1
	v_cndmask_b32_e64 v97, v98, v99, s[4:5]
	v_mul_f32_e32 v98, 0x37800000, v97
	v_cndmask_b32_e32 v97, v97, v98, vcc
	v_cmp_class_f32_e32 vcc, v96, v147
	s_nop 1
	v_cndmask_b32_e32 v96, v97, v96, vcc
	v_div_scale_f32 v97, s[4:5], v96, v96, 1.0
	v_rcp_f32_e32 v98, v97
	s_nop 0
	v_fma_f32 v99, -v97, v98, 1.0
	v_fmac_f32_e32 v98, v99, v98
	v_div_scale_f32 v99, vcc, 1.0, v96, 1.0
	v_mul_f32_e32 v100, v99, v98
	v_fma_f32 v101, -v97, v100, v99
	v_fmac_f32_e32 v100, v101, v98
	v_fma_f32 v97, -v97, v100, v99
	v_div_fmas_f32 v97, v97, v98, v100
	v_div_fixup_f32 v96, v97, v96, 1.0
	v_mul_f32_e32 v32, v48, v96
	v_mul_f32_e32 v33, v49, v96
	v_mul_f32_e32 v34, v50, v96
	v_mul_f32_e32 v35, v51, v96
	v_mul_f32_e32 v36, v52, v96
	v_mul_f32_e32 v37, v53, v96
	v_mul_f32_e32 v38, v54, v96
	v_mul_f32_e32 v39, v55, v96
	v_mul_f32_e32 v40, v56, v96
	v_mul_f32_e32 v41, v57, v96
	v_mul_f32_e32 v42, v58, v96
	v_mul_f32_e32 v43, v59, v96
	v_mul_f32_e32 v44, v60, v96
	v_mul_f32_e32 v45, v61, v96
	v_mul_f32_e32 v46, v62, v96
	v_mul_f32_e32 v47, v63, v96
	v_mul_f32_e32 v32, v128, v32
	v_mul_f32_e32 v33, v129, v33
	v_mul_f32_e32 v34, v130, v34
	v_mul_f32_e32 v35, v131, v35
	v_mul_f32_e32 v36, v132, v36
	v_mul_f32_e32 v37, v133, v37
	v_mul_f32_e32 v38, v134, v38
	v_mul_f32_e32 v39, v135, v39
	v_mul_f32_e32 v40, v136, v40
	v_mul_f32_e32 v41, v137, v41
	v_mul_f32_e32 v42, v138, v42
	v_mul_f32_e32 v43, v139, v43
	v_mul_f32_e32 v44, v140, v44
	v_mul_f32_e32 v45, v141, v45
	v_mul_f32_e32 v46, v142, v46
	v_mul_f32_e32 v47, v143, v47
	v_cvt_pk_bf16_f32 v148, v32, v33
	v_cvt_pk_bf16_f32 v149, v34, v35
	global_store_dwordx2 v145, v[148:149], s[42:43] offset:0
	v_cvt_pk_bf16_f32 v150, v36, v37
	v_cvt_pk_bf16_f32 v151, v38, v39
	global_store_dwordx2 v145, v[150:151], s[42:43] offset:512
	v_cvt_pk_bf16_f32 v152, v40, v41
	v_cvt_pk_bf16_f32 v153, v42, v43
	global_store_dwordx2 v145, v[152:153], s[42:43] offset:1024
	v_cvt_pk_bf16_f32 v154, v44, v45
	v_cvt_pk_bf16_f32 v155, v46, v47
	global_store_dwordx2 v145, v[154:155], s[42:43] offset:1536
	s_add_u32 s40, s40, 0x1000
	s_addc_u32 s41, s41, 0
	s_add_u32 s42, s42, 0x800
	s_addc_u32 s43, s43, 0
	s_sub_u32 s21, s28, 44
	s_cmp_lt_u32 s21, 16
	s_cbranch_scc0 .Lfrp3_end
	s_waitcnt vmcnt(0)
	v_cmp_eq_u32_e32 vcc, 0, v180
	s_and_saveexec_b64 s[46:47], vcc
	s_cbranch_execz .Lfrp3_ws_done
	v_mov_b32_e32 v230, 0
	s_add_u32 s44, s30, 0x3180500
	s_addc_u32 s45, s31, 0
.Lfrp3_ws_spin:
	global_load_dword v231, v230, s[44:45] sc1
	s_waitcnt vmcnt(0)
	v_cmp_gt_u32_e32 vcc, 44, v231
	s_cbranch_vccz .Lfrp3_ws_ok
	s_sleep 2
	s_branch .Lfrp3_ws_spin

; __device__ __forceinline__ const float* xrow_ptr(const Ctx& p, int row) { return row < MPR ? p.in(0) + (size_t)row * DM : p.in(1) + (size_t)(row - MPR) * DM; }
; __device__ __forceinline__ void phase_rowpass(const Ctx& p, const float* F, int base_is_x, float alpha, const float* gpost, const float* gnext, bf16_t* XN, const float* PART, int nsplit) {
;     ...
;     auto loadrow = [&](int m, f32x4 (&f)[4], f32x4 (&b)[4]) {
;         const f32x4* fr = (const f32x4*)(F + (size_t)m * DM) + lane;
;         const f32x4* br = (const f32x4*)(base_is_x ? xrow_ptr(p, m) : H + (size_t)m * DM) + lane;
; #pragma unroll
;         for (int j = 0; j < 4; ++j) { b[j] = br[64 * j];
;             if (m < MPR) f[j] = fr[64 * j];
;             else { f[j] = (f32x4){0.f, 0.f, 0.f, 0.f};
;                 for (int ks = 0; ks < nsplit; ++ks) f[j] = f[j] + ((const f32x4*)(PART + ((size_t)ks * 128 + (m - MPR)) * DM))[lane + 64 * j]; } }
.Lfrp3_ws_done:
	s_or_b64 exec, exec, s[46:47]
	s_barrier
	s_lshl_b32 s19, s21, 3
	s_add_i32 s19, s19, s20
	s_add_i32 s23, s19, 0x4000
	s_lshl_b32 s21, s23, 12
	s_add_u32 s40, s8, s21
	s_addc_u32 s41, s9, 0
	s_lshl_b32 s22, s23, 11
	s_add_u32 s42, s30, s22
	s_addc_u32 s43, s31, 0
	s_add_u32 s42, s42, 0x3200000
	s_addc_u32 s43, s43, 0
	s_lshl_b32 s21, s19, 12
	s_add_u32 s24, s30, s21
	s_addc_u32 s25, s31, 0
	s_add_u32 s24, s24, 0xf000000
	s_addc_u32 s25, s25, 0
	s_add_u32 s26, s16, s21
	s_addc_u32 s27, s17, 0
	global_load_dwordx4 v[200:203], v144, s[26:27] offset:0
	global_load_dwordx4 v[204:207], v144, s[26:27] offset:1024
	global_load_dwordx4 v[208:211], v144, s[26:27] offset:2048
	global_load_dwordx4 v[212:215], v144, s[26:27] offset:3072
	s_mov_b32 s34, s24
	s_mov_b32 s35, s25
	global_load_dwordx4 v[0:3], v144, s[34:35] offset:0
	global_load_dwordx4 v[44:47], v144, s[34:35] offset:1024
	s_add_u32 s34, s34, 0x80000
	s_addc_u32 s35, s35, 0
	global_load_dwordx4 v[4:7], v144, s[34:35] offset:0
	global_load_dwordx4 v[48:51], v144, s[34:35] offset:1024
	s_add_u32 s34, s34, 0x80000
	s_addc_u32 s35, s35, 0
	global_load_dwordx4 v[8:11], v144, s[34:35] offset:0
	global_load_dwordx4 v[52:55], v144, s[34:35] offset:1024
	s_add_u32 s34, s34, 0x80000
	s_addc_u32 s35, s35, 0
	global_load_dwordx4 v[12:15], v144, s[34:35] offset:0
	global_load_dwordx4 v[56:59], v144, s[34:35] offset:1024
	s_add_u32 s34, s34, 0x80000
	s_addc_u32 s35, s35, 0
	global_load_dwordx4 v[16:19], v144, s[34:35] offset:0
	global_load_dwordx4 v[60:63], v144, s[34:35] offset:1024
	s_add_u32 s34, s34, 0x80000
	s_addc_u32 s35, s35, 0
	global_load_dwordx4 v[20:23], v144, s[34:35] offset:0
	global_load_dwordx4 v[64:67], v144, s[34:35] offset:1024
	s_add_u32 s34, s34, 0x80000
	s_addc_u32 s35, s35, 0
	global_load_dwordx4 v[24:27], v144, s[34:35] offset:0
	global_load_dwordx4 v[68:71], v144, s[34:35] offset:1024
	s_add_u32 s34, s34, 0x80000
	s_addc_u32 s35, s35, 0
	global_load_dwordx4 v[28:31], v144, s[34:35] offset:0
	global_load_dwordx4 v[72:75], v144, s[34:35] offset:1024
	s_add_u32 s34, s34, 0x80000
	s_addc_u32 s35, s35, 0
	global_load_dwordx4 v[32:35], v144, s[34:35] offset:0
	global_load_dwordx4 v[76:79], v144, s[34:35] offset:1024
	s_add_u32 s34, s34, 0x80000
	s_addc_u32 s35, s35, 0
	global_load_dwordx4 v[36:39], v144, s[34:35] offset:0
	global_load_dwordx4 v[80:83], v144, s[34:35] offset:1024
	s_add_u32 s34, s34, 0x80000
	s_addc_u32 s35, s35, 0
	global_load_dwordx4 v[40:43], v144, s[34:35] offset:0
	global_load_dwordx4 v[84:87], v144, s[34:35] offset:1024
	s_waitcnt vmcnt(21)
	v_mov_b32_e32 v184, v0
	v_mov_b32_e32 v185, v1
	v_mov_b32_e32 v186, v2
	v_mov_b32_e32 v187, v3
	s_waitcnt vmcnt(19)
	v_add_f32_e32 v184, v184, v4
	v_add_f32_e32 v185, v185, v5
	v_add_f32_e32 v186, v186, v6
	v_add_f32_e32 v187, v187, v7
	s_waitcnt vmcnt(17)
	v_add_f32_e32 v184, v184, v8
	v_add_f32_e32 v185, v185, v9
	v_add_f32_e32 v186, v186, v10
	v_add_f32_e32 v187, v187, v11
	s_waitcnt vmcnt(15)
	v_add_f32_e32 v184, v184, v12
	v_add_f32_e32 v185, v185, v13
	v_add_f32_e32 v186, v186, v14
	v_add_f32_e32 v187, v187, v15
	s_waitcnt vmcnt(13)
	v_add_f32_e32 v184, v184, v16
	v_add_f32_e32 v185, v185, v17
	v_add_f32_e32 v186, v186, v18
	v_add_f32_e32 v187, v187, v19
	s_waitcnt vmcnt(11)
	v_add_f32_e32 v184, v184, v20
	v_add_f32_e32 v185, v185, v21
	v_add_f32_e32 v186, v186, v22
	v_add_f32_e32 v187, v187, v23
	s_waitcnt vmcnt(9)
	v_add_f32_e32 v184, v184, v24
	v_add_f32_e32 v185, v185, v25
	v_add_f32_e32 v186, v186, v26
	v_add_f32_e32 v187, v187, v27
	s_waitcnt vmcnt(7)
	v_add_f32_e32 v184, v184, v28
	v_add_f32_e32 v185, v185, v29
	v_add_f32_e32 v186, v186, v30
	v_add_f32_e32 v187, v187, v31
	s_waitcnt vmcnt(5)
	v_add_f32_e32 v184, v184, v32
	v_add_f32_e32 v185, v185, v33
	v_add_f32_e32 v186, v186, v34
	v_add_f32_e32 v187, v187, v35
	s_waitcnt vmcnt(3)
	v_add_f32_e32 v184, v184, v36
	v_add_f32_e32 v185, v185, v37
	v_add_f32_e32 v186, v186, v38
	v_add_f32_e32 v187, v187, v39
	s_waitcnt vmcnt(1)
	v_add_f32_e32 v184, v184, v40
	v_add_f32_e32 v185, v185, v41
	v_add_f32_e32 v186, v186, v42
	v_add_f32_e32 v187, v187, v43
	s_waitcnt vmcnt(20)
	v_mov_b32_e32 v188, v44
	v_mov_b32_e32 v189, v45
	v_mov_b32_e32 v190, v46
	v_mov_b32_e32 v191, v47
	s_waitcnt vmcnt(18)
	v_add_f32_e32 v188, v188, v48
	v_add_f32_e32 v189, v189, v49
	v_add_f32_e32 v190, v190, v50
	v_add_f32_e32 v191, v191, v51
	s_waitcnt vmcnt(16)
	v_add_f32_e32 v188, v188, v52
	v_add_f32_e32 v189, v189, v53
	v_add_f32_e32 v190, v190, v54
	v_add_f32_e32 v191, v191, v55
	s_waitcnt vmcnt(14)
	v_add_f32_e32 v188, v188, v56
	v_add_f32_e32 v189, v189, v57
	v_add_f32_e32 v190, v190, v58
	v_add_f32_e32 v191, v191, v59
	s_waitcnt vmcnt(12)
	v_add_f32_e32 v188, v188, v60
	v_add_f32_e32 v189, v189, v61
	v_add_f32_e32 v190, v190, v62
	v_add_f32_e32 v191, v191, v63
	s_waitcnt vmcnt(10)
	v_add_f32_e32 v188, v188, v64
	v_add_f32_e32 v189, v189, v65
	v_add_f32_e32 v190, v190, v66
	v_add_f32_e32 v191, v191, v67
	s_waitcnt vmcnt(8)
	v_add_f32_e32 v188, v188, v68
	v_add_f32_e32 v189, v189, v69
	v_add_f32_e32 v190, v190, v70
	v_add_f32_e32 v191, v191, v71
	s_waitcnt vmcnt(6)
	v_add_f32_e32 v188, v188, v72
	v_add_f32_e32 v189, v189, v73
	v_add_f32_e32 v190, v190, v74
	v_add_f32_e32 v191, v191, v75
	s_waitcnt vmcnt(4)
	v_add_f32_e32 v188, v188, v76
	v_add_f32_e32 v189, v189, v77
	v_add_f32_e32 v190, v190, v78
	v_add_f32_e32 v191, v191, v79
	s_waitcnt vmcnt(2)
	v_add_f32_e32 v188, v188, v80
	v_add_f32_e32 v189, v189, v81
	v_add_f32_e32 v190, v190, v82
	v_add_f32_e32 v191, v191, v83
	s_waitcnt vmcnt(0)
; __device__ __forceinline__ void phase_rowpass(const Ctx& p, const float* F, int base_is_x, float alpha, const float* gpost, const float* gnext, bf16_t* XN, const float* PART, int nsplit) {
;     ...
;         for (int j = 0; j < 4; ++j) { b[j] = br[64 * j];
;             if (m < MPR) f[j] = fr[64 * j];
;             else { f[j] = (f32x4){0.f, 0.f, 0.f, 0.f};
;                 for (int ks = 0; ks < nsplit; ++ks) f[j] = f[j] + ((const f32x4*)(PART + ((size_t)ks * 128 + (m - MPR)) * DM))[lane + 64 * j]; } }
	v_add_f32_e32 v188, v188, v84
	v_add_f32_e32 v189, v189, v85
	v_add_f32_e32 v190, v190, v86
	v_add_f32_e32 v191, v191, v87
	s_mov_b32 s34, s24
	s_mov_b32 s35, s25
	global_load_dwordx4 v[0:3], v144, s[34:35] offset:2048
	global_load_dwordx4 v[44:47], v144, s[34:35] offset:3072
	s_add_u32 s34, s34, 0x80000
	s_addc_u32 s35, s35, 0
	global_load_dwordx4 v[4:7], v144, s[34:35] offset:2048
	global_load_dwordx4 v[48:51], v144, s[34:35] offset:3072
	s_add_u32 s34, s34, 0x80000
	s_addc_u32 s35, s35, 0
	global_load_dwordx4 v[8:11], v144, s[34:35] offset:2048
	global_load_dwordx4 v[52:55], v144, s[34:35] offset:3072
	s_add_u32 s34, s34, 0x80000
	s_addc_u32 s35, s35, 0
	global_load_dwordx4 v[12:15], v144, s[34:35] offset:2048
	global_load_dwordx4 v[56:59], v144, s[34:35] offset:3072
	s_add_u32 s34, s34, 0x80000
	s_addc_u32 s35, s35, 0
	global_load_dwordx4 v[16:19], v144, s[34:35] offset:2048
	global_load_dwordx4 v[60:63], v144, s[34:35] offset:3072
	s_add_u32 s34, s34, 0x80000
	s_addc_u32 s35, s35, 0
	global_load_dwordx4 v[20:23], v144, s[34:35] offset:2048
	global_load_dwordx4 v[64:67], v144, s[34:35] offset:3072
	s_add_u32 s34, s34, 0x80000
	s_addc_u32 s35, s35, 0
	global_load_dwordx4 v[24:27], v144, s[34:35] offset:2048
	global_load_dwordx4 v[68:71], v144, s[34:35] offset:3072
	s_add_u32 s34, s34, 0x80000
	s_addc_u32 s35, s35, 0
	global_load_dwordx4 v[28:31], v144, s[34:35] offset:2048
	global_load_dwordx4 v[72:75], v144, s[34:35] offset:3072
	s_add_u32 s34, s34, 0x80000
	s_addc_u32 s35, s35, 0
	global_load_dwordx4 v[32:35], v144, s[34:35] offset:2048
	global_load_dwordx4 v[76:79], v144, s[34:35] offset:3072
	s_add_u32 s34, s34, 0x80000
	s_addc_u32 s35, s35, 0
	global_load_dwordx4 v[36:39], v144, s[34:35] offset:2048
	global_load_dwordx4 v[80:83], v144, s[34:35] offset:3072
	s_add_u32 s34, s34, 0x80000
	s_addc_u32 s35, s35, 0
	global_load_dwordx4 v[40:43], v144, s[34:35] offset:2048
	global_load_dwordx4 v[84:87], v144, s[34:35] offset:3072
	s_waitcnt vmcnt(21)
	v_mov_b32_e32 v192, v0
	v_mov_b32_e32 v193, v1
	v_mov_b32_e32 v194, v2
	v_mov_b32_e32 v195, v3
	s_waitcnt vmcnt(19)
	v_add_f32_e32 v192, v192, v4
	v_add_f32_e32 v193, v193, v5
	v_add_f32_e32 v194, v194, v6
	v_add_f32_e32 v195, v195, v7
	s_waitcnt vmcnt(17)
	v_add_f32_e32 v192, v192, v8
	v_add_f32_e32 v193, v193, v9
	v_add_f32_e32 v194, v194, v10
	v_add_f32_e32 v195, v195, v11
	s_waitcnt vmcnt(15)
	v_add_f32_e32 v192, v192, v12
	v_add_f32_e32 v193, v193, v13
	v_add_f32_e32 v194, v194, v14
	v_add_f32_e32 v195, v195, v15
	s_waitcnt vmcnt(13)
	v_add_f32_e32 v192, v192, v16
	v_add_f32_e32 v193, v193, v17
	v_add_f32_e32 v194, v194, v18
	v_add_f32_e32 v195, v195, v19
	s_waitcnt vmcnt(11)
	v_add_f32_e32 v192, v192, v20
	v_add_f32_e32 v193, v193, v21
	v_add_f32_e32 v194, v194, v22
	v_add_f32_e32 v195, v195, v23
	s_waitcnt vmcnt(9)
	v_add_f32_e32 v192, v192, v24
	v_add_f32_e32 v193, v193, v25
	v_add_f32_e32 v194, v194, v26
	v_add_f32_e32 v195, v195, v27
	s_waitcnt vmcnt(7)
	v_add_f32_e32 v192, v192, v28
	v_add_f32_e32 v193, v193, v29
	v_add_f32_e32 v194, v194, v30
	v_add_f32_e32 v195, v195, v31
	s_waitcnt vmcnt(5)
	v_add_f32_e32 v192, v192, v32
	v_add_f32_e32 v193, v193, v33
	v_add_f32_e32 v194, v194, v34
	v_add_f32_e32 v195, v195, v35
	s_waitcnt vmcnt(3)
	v_add_f32_e32 v192, v192, v36
	v_add_f32_e32 v193, v193, v37
	v_add_f32_e32 v194, v194, v38
	v_add_f32_e32 v195, v195, v39
	s_waitcnt vmcnt(1)
	v_add_f32_e32 v192, v192, v40
	v_add_f32_e32 v193, v193, v41
	v_add_f32_e32 v194, v194, v42
	v_add_f32_e32 v195, v195, v43
	s_waitcnt vmcnt(20)
	v_mov_b32_e32 v196, v44
	v_mov_b32_e32 v197, v45
	v_mov_b32_e32 v198, v46
	v_mov_b32_e32 v199, v47
	s_waitcnt vmcnt(18)
	v_add_f32_e32 v196, v196, v48
	v_add_f32_e32 v197, v197, v49
	v_add_f32_e32 v198, v198, v50
	v_add_f32_e32 v199, v199, v51
	s_waitcnt vmcnt(16)
	v_add_f32_e32 v196, v196, v52
	v_add_f32_e32 v197, v197, v53
	v_add_f32_e32 v198, v198, v54
	v_add_f32_e32 v199, v199, v55
	s_waitcnt vmcnt(14)
	v_add_f32_e32 v196, v196, v56
	v_add_f32_e32 v197, v197, v57
	v_add_f32_e32 v198, v198, v58
	v_add_f32_e32 v199, v199, v59
	s_waitcnt vmcnt(12)
	v_add_f32_e32 v196, v196, v60
	v_add_f32_e32 v197, v197, v61
	v_add_f32_e32 v198, v198, v62
	v_add_f32_e32 v199, v199, v63
	s_waitcnt vmcnt(10)
	v_add_f32_e32 v196, v196, v64
	v_add_f32_e32 v197, v197, v65
	v_add_f32_e32 v198, v198, v66
	v_add_f32_e32 v199, v199, v67
	s_waitcnt vmcnt(8)
	v_add_f32_e32 v196, v196, v68
	v_add_f32_e32 v197, v197, v69
	v_add_f32_e32 v198, v198, v70
	v_add_f32_e32 v199, v199, v71
	s_waitcnt vmcnt(6)
	v_add_f32_e32 v196, v196, v72
	v_add_f32_e32 v197, v197, v73
	v_add_f32_e32 v198, v198, v74
	v_add_f32_e32 v199, v199, v75
	s_waitcnt vmcnt(4)
	v_add_f32_e32 v196, v196, v76
	v_add_f32_e32 v197, v197, v77
	v_add_f32_e32 v198, v198, v78
	v_add_f32_e32 v199, v199, v79
	s_waitcnt vmcnt(2)
	v_add_f32_e32 v196, v196, v80
	v_add_f32_e32 v197, v197, v81
	v_add_f32_e32 v198, v198, v82
	v_add_f32_e32 v199, v199, v83
	s_waitcnt vmcnt(0)
	v_add_f32_e32 v196, v196, v84
	v_add_f32_e32 v197, v197, v85
	v_add_f32_e32 v198, v198, v86
	v_add_f32_e32 v199, v199, v87
	s_waitcnt vmcnt(44)
; __device__ __forceinline__ void phase_rowpass(const Ctx& p, const float* F, int base_is_x, float alpha, const float* gpost, const float* gnext, bf16_t* XN, const float* PART, int nsplit) {
;     ...
;         float s = 0.f;
; #pragma unroll
;         for (int j = 0; j < 4; ++j) s += (f[j].x * f[j].x + f[j].y * f[j].y) + (f[j].z * f[j].z + f[j].w * f[j].w);
;         const float rs = alpha / sqrtf(wave_sum_fast(s) * (1.f / DM) + EPS);
;         float s2 = 0.f;
; #pragma unroll
;         for (int j = 0; j < 4; ++j) { b[j] = b[j] + f[j] * rs * gp[j]; s2 += (b[j].x * b[j].x + b[j].y * b[j].y) + (b[j].z * b[j].z + b[j].w * b[j].w);
;             ((f32x4*)(H + (size_t)m * DM))[lane + 64 * j] = b[j]; }
	v_mul_f32_e32 v96, v185, v185
	v_mul_f32_e32 v98, v187, v187
	v_fmac_f32_e32 v96, v184, v184
	v_fmac_f32_e32 v98, v186, v186
	v_add_f32_e32 v96, v96, v98
	v_mul_f32_e32 v97, v189, v189
	v_mul_f32_e32 v98, v191, v191
	v_fmac_f32_e32 v97, v188, v188
	v_fmac_f32_e32 v98, v190, v190
	v_add_f32_e32 v97, v97, v98
	v_add_f32_e32 v96, v97, v96
	v_mul_f32_e32 v97, v193, v193
	v_mul_f32_e32 v98, v195, v195
	v_fmac_f32_e32 v97, v192, v192
	v_fmac_f32_e32 v98, v194, v194
	v_add_f32_e32 v97, v97, v98
	v_add_f32_e32 v96, v97, v96
	v_mul_f32_e32 v97, v197, v197
	v_mul_f32_e32 v98, v199, v199
	v_fmac_f32_e32 v97, v196, v196
	v_fmac_f32_e32 v98, v198, v198
	v_add_f32_e32 v97, v97, v98
	v_add_f32_e32 v96, v97, v96
	s_nop 1
	v_add_f32_dpp v96, v96, v96 quad_perm:[1,0,3,2] row_mask:0xf bank_mask:0xf bound_ctrl:1
	s_nop 1
	v_add_f32_dpp v96, v96, v96 quad_perm:[2,3,0,1] row_mask:0xf bank_mask:0xf bound_ctrl:1
	s_nop 1
	v_add_f32_dpp v96, v96, v96 row_half_mirror row_mask:0xf bank_mask:0xf bound_ctrl:1
	s_nop 1
	v_add_f32_dpp v96, v96, v96 row_mirror row_mask:0xf bank_mask:0xf bound_ctrl:1
	v_mov_b32_e32 v97, v96
	s_nop 1
	v_permlane16_swap_b32_e32 v96, v97
	v_add_f32_e32 v96, v96, v97
	v_mov_b32_e32 v97, v96
	s_nop 1
	v_permlane32_swap_b32_e32 v96, v97
	v_add_f32_e32 v96, v96, v97
	v_fmamk_f32 v96, v96, 0x3a800000, v146
	v_mul_f32_e32 v97, 0x4f800000, v96
	v_cmp_gt_f32_e32 vcc, s33, v96
	s_nop 1
	v_cndmask_b32_e32 v96, v96, v97, vcc
	v_sqrt_f32_e32 v97, v96
	s_nop 0
	v_add_u32_e32 v98, -1, v97
	v_fma_f32 v99, -v98, v97, v96
	v_cmp_ge_f32_e64 s[4:5], 0, v99
	v_add_u32_e32 v99, 1, v97
	s_nop 0
	v_cndmask_b32_e64 v98, v97, v98, s[4:5]
	v_fma_f32 v97, -v99, v97, v96
	v_cmp_lt_f32_e64 s[4:5], 0, v97
	s_nop 1
	v_cndmask_b32_e64 v97, v98, v99, s[4:5]
	v_mul_f32_e32 v98, 0x37800000, v97
	v_cndmask_b32_e32 v97, v97, v98, vcc
	v_cmp_class_f32_e32 vcc, v96, v147
	s_nop 1
	v_cndmask_b32_e32 v96, v97, v96, vcc
	v_div_scale_f32 v97, s[4:5], v96, v96, 0.5
	v_rcp_f32_e32 v98, v97
	s_nop 0
	v_fma_f32 v99, -v97, v98, 1.0
	v_fmac_f32_e32 v98, v99, v98
	v_div_scale_f32 v99, vcc, 0.5, v96, 0.5
	v_mul_f32_e32 v100, v99, v98
	v_fma_f32 v101, -v97, v100, v99
	v_fmac_f32_e32 v100, v101, v98
	v_fma_f32 v97, -v97, v100, v99
	v_div_fmas_f32 v97, v97, v98, v100
	v_div_fixup_f32 v96, v97, v96, 0.5
	v_mul_f32_e32 v184, v184, v96
	v_mul_f32_e32 v185, v185, v96
	v_mul_f32_e32 v186, v186, v96
	v_mul_f32_e32 v187, v187, v96
	v_mul_f32_e32 v188, v188, v96
	v_mul_f32_e32 v189, v189, v96
	v_mul_f32_e32 v190, v190, v96
	v_mul_f32_e32 v191, v191, v96
	v_mul_f32_e32 v192, v192, v96
	v_mul_f32_e32 v193, v193, v96
	v_mul_f32_e32 v194, v194, v96
	v_mul_f32_e32 v195, v195, v96
	v_mul_f32_e32 v196, v196, v96
	v_mul_f32_e32 v197, v197, v96
	v_mul_f32_e32 v198, v198, v96
	v_mul_f32_e32 v199, v199, v96
	v_fmac_f32_e32 v200, v112, v184
	v_fmac_f32_e32 v201, v113, v185
	v_fmac_f32_e32 v202, v114, v186
	v_fmac_f32_e32 v203, v115, v187
	v_fmac_f32_e32 v204, v116, v188
	v_fmac_f32_e32 v205, v117, v189
	v_fmac_f32_e32 v206, v118, v190
	v_fmac_f32_e32 v207, v119, v191
	v_fmac_f32_e32 v208, v120, v192
	v_fmac_f32_e32 v209, v121, v193
	v_fmac_f32_e32 v210, v122, v194
	v_fmac_f32_e32 v211, v123, v195
	v_fmac_f32_e32 v212, v124, v196
	v_fmac_f32_e32 v213, v125, v197
	v_fmac_f32_e32 v214, v126, v198
	v_fmac_f32_e32 v215, v127, v199
	global_store_dwordx4 v144, v[200:203], s[40:41] offset:0
	global_store_dwordx4 v144, v[204:207], s[40:41] offset:1024
	global_store_dwordx4 v144, v[208:211], s[40:41] offset:2048
	global_store_dwordx4 v144, v[212:215], s[40:41] offset:3072
	v_mul_f32_e32 v96, v201, v201
	v_mul_f32_e32 v98, v203, v203
	v_fmac_f32_e32 v96, v200, v200
	v_fmac_f32_e32 v98, v202, v202
	v_add_f32_e32 v96, v96, v98
; __device__ __forceinline__ unsigned pk2(float lo, float hi) { f32x2 v = {lo, hi}; bf16x2_t b = __builtin_convertvector(v, bf16x2_t); return __builtin_bit_cast(unsigned, b); }
; __device__ __forceinline__ void phase_rowpass(const Ctx& p, const float* F, int base_is_x, float alpha, const float* gpost, const float* gnext, bf16_t* XN, const float* PART, int nsplit) {
;     ...
;         float s2 = 0.f;
; #pragma unroll
;         for (int j = 0; j < 4; ++j) { b[j] = b[j] + f[j] * rs * gp[j]; s2 += (b[j].x * b[j].x + b[j].y * b[j].y) + (b[j].z * b[j].z + b[j].w * b[j].w);
;             ((f32x4*)(H + (size_t)m * DM))[lane + 64 * j] = b[j]; }
;         if (gnext) {
;             const float r2 = 1.f / sqrtf(wave_sum_fast(s2) * (1.f / DM) + EPS);
;             u32x2* o8 = (u32x2*)(XN + (size_t)m * DM) + lane;
; #pragma unroll
;             for (int j = 0; j < 4; ++j) { u32x2 w; w.x = pk2(b[j].x * r2 * gn[j].x, b[j].y * r2 * gn[j].y); w.y = pk2(b[j].z * r2 * gn[j].z, b[j].w * r2 * gn[j].w); o8[64 * j] = w; }
;         }
	v_mul_f32_e32 v97, v205, v205
	v_mul_f32_e32 v98, v207, v207
	v_fmac_f32_e32 v97, v204, v204
	v_fmac_f32_e32 v98, v206, v206
	v_add_f32_e32 v97, v97, v98
	v_add_f32_e32 v96, v97, v96
	v_mul_f32_e32 v97, v209, v209
	v_mul_f32_e32 v98, v211, v211
	v_fmac_f32_e32 v97, v208, v208
	v_fmac_f32_e32 v98, v210, v210
	v_add_f32_e32 v97, v97, v98
	v_add_f32_e32 v96, v97, v96
	v_mul_f32_e32 v97, v213, v213
	v_mul_f32_e32 v98, v215, v215
	v_fmac_f32_e32 v97, v212, v212
	v_fmac_f32_e32 v98, v214, v214
	v_add_f32_e32 v97, v97, v98
	v_add_f32_e32 v96, v97, v96
	s_nop 1
	v_add_f32_dpp v96, v96, v96 quad_perm:[1,0,3,2] row_mask:0xf bank_mask:0xf bound_ctrl:1
	s_nop 1
	v_add_f32_dpp v96, v96, v96 quad_perm:[2,3,0,1] row_mask:0xf bank_mask:0xf bound_ctrl:1
	s_nop 1
	v_add_f32_dpp v96, v96, v96 row_half_mirror row_mask:0xf bank_mask:0xf bound_ctrl:1
	s_nop 1
	v_add_f32_dpp v96, v96, v96 row_mirror row_mask:0xf bank_mask:0xf bound_ctrl:1
	v_mov_b32_e32 v97, v96
	s_nop 1
	v_permlane16_swap_b32_e32 v96, v97
	v_add_f32_e32 v96, v96, v97
	v_mov_b32_e32 v97, v96
	s_nop 1
	v_permlane32_swap_b32_e32 v96, v97
	v_add_f32_e32 v96, v96, v97
	v_fmamk_f32 v96, v96, 0x3a800000, v146
	v_mul_f32_e32 v97, 0x4f800000, v96
	v_cmp_gt_f32_e32 vcc, s33, v96
	s_nop 1
	v_cndmask_b32_e32 v96, v96, v97, vcc
	v_sqrt_f32_e32 v97, v96
	s_nop 0
	v_add_u32_e32 v98, -1, v97
	v_fma_f32 v99, -v98, v97, v96
	v_cmp_ge_f32_e64 s[4:5], 0, v99
	v_add_u32_e32 v99, 1, v97
	s_nop 0
	v_cndmask_b32_e64 v98, v97, v98, s[4:5]
	v_fma_f32 v97, -v99, v97, v96
	v_cmp_lt_f32_e64 s[4:5], 0, v97
	s_nop 1
	v_cndmask_b32_e64 v97, v98, v99, s[4:5]
	v_mul_f32_e32 v98, 0x37800000, v97
	v_cndmask_b32_e32 v97, v97, v98, vcc
	v_cmp_class_f32_e32 vcc, v96, v147
	s_nop 1
	v_cndmask_b32_e32 v96, v97, v96, vcc
	v_div_scale_f32 v97, s[4:5], v96, v96, 1.0
	v_rcp_f32_e32 v98, v97
	s_nop 0
	v_fma_f32 v99, -v97, v98, 1.0
	v_fmac_f32_e32 v98, v99, v98
	v_div_scale_f32 v99, vcc, 1.0, v96, 1.0
	v_mul_f32_e32 v100, v99, v98
	v_fma_f32 v101, -v97, v100, v99
	v_fmac_f32_e32 v100, v101, v98
	v_fma_f32 v97, -v97, v100, v99
	v_div_fmas_f32 v97, v97, v98, v100
	v_div_fixup_f32 v96, v97, v96, 1.0
	v_mul_f32_e32 v184, v200, v96
	v_mul_f32_e32 v185, v201, v96
	v_mul_f32_e32 v186, v202, v96
	v_mul_f32_e32 v187, v203, v96
	v_mul_f32_e32 v188, v204, v96
	v_mul_f32_e32 v189, v205, v96
	v_mul_f32_e32 v190, v206, v96
	v_mul_f32_e32 v191, v207, v96
	v_mul_f32_e32 v192, v208, v96
	v_mul_f32_e32 v193, v209, v96
	v_mul_f32_e32 v194, v210, v96
	v_mul_f32_e32 v195, v211, v96
	v_mul_f32_e32 v196, v212, v96
	v_mul_f32_e32 v197, v213, v96
	v_mul_f32_e32 v198, v214, v96
	v_mul_f32_e32 v199, v215, v96
	v_mul_f32_e32 v184, v128, v184
	v_mul_f32_e32 v185, v129, v185
	v_mul_f32_e32 v186, v130, v186
	v_mul_f32_e32 v187, v131, v187
	v_mul_f32_e32 v188, v132, v188
	v_mul_f32_e32 v189, v133, v189
	v_mul_f32_e32 v190, v134, v190
	v_mul_f32_e32 v191, v135, v191
	v_mul_f32_e32 v192, v136, v192
	v_mul_f32_e32 v193, v137, v193
	v_mul_f32_e32 v194, v138, v194
	v_mul_f32_e32 v195, v139, v195
	v_mul_f32_e32 v196, v140, v196
	v_mul_f32_e32 v197, v141, v197
	v_mul_f32_e32 v198, v142, v198
	v_mul_f32_e32 v199, v143, v199
	v_cvt_pk_bf16_f32 v148, v184, v185
	v_cvt_pk_bf16_f32 v149, v186, v187
	global_store_dwordx2 v145, v[148:149], s[42:43] offset:0
	v_cvt_pk_bf16_f32 v150, v188, v189
	v_cvt_pk_bf16_f32 v151, v190, v191
	global_store_dwordx2 v145, v[150:151], s[42:43] offset:512
	v_cvt_pk_bf16_f32 v152, v192, v193
	v_cvt_pk_bf16_f32 v153, v194, v195
	global_store_dwordx2 v145, v[152:153], s[42:43] offset:1024
	v_cvt_pk_bf16_f32 v154, v196, v197
	v_cvt_pk_bf16_f32 v155, v198, v199
	global_store_dwordx2 v145, v[154:155], s[42:43] offset:1536
.Lfrp3_end:
	s_mov_b64 s[6:7], -1
